# GEMM K-loops: per-segment s_setprio flips removed (both wave halves at equal priority)
# speedup vs baseline: 1.0143x; 1.0058x over previous
; #define PG8_STAGE(bufoff, gbase, voff) do { _Pragma("unroll") for (int _i = 0; _i < 2; ++_i) \
;         __builtin_amdgcn_global_load_lds((const unsigned*)((const char*)(gbase) + (voff)[_i]), (PG8_LAS unsigned*)(lds + (bufoff) + ldsw + _i * 8192), 16, 0, 0); } while (0)
; #define PG8_LDA(dst, b, h) do { _Pragma("unroll") for (int m = 0; m < 4; ++m) _Pragma("unroll") for (int k = 0; k < 2; ++k) dst[m][k] = *(const PG8_LAS bf16x8*)(lds + PG8_SA(b, h) + aoff + m * 2048 + k * 1024); } while (0)
; #define PG8_LDB(dst, b, h) do { _Pragma("unroll") for (int n = 0; n < 2; ++n) _Pragma("unroll") for (int k = 0; k < 2; ++k) dst[n][k] = *(const PG8_LAS bf16x8*)(lds + PG8_SB(b, h) + boff + n * 2048 + k * 1024); } while (0)
; #define PG8_MMA(ai, bj, At, Bt) do { __builtin_amdgcn_s_setprio(1); _Pragma("unroll") for (int m = 0; m < 4; ++m) _Pragma("unroll") for (int n = 0; n < 2; ++n) _Pragma("unroll") for (int k = 0; k < 2; ++k) \
;         acc[ai][bj][m][n] = __builtin_amdgcn_mfma_f32_16x16x32_bf16(Bt[n][k], At[m][k], acc[ai][bj][m][n], 0, 0, 0); __builtin_amdgcn_s_setprio(0); } while (0)
; #define PG8_BAR __builtin_amdgcn_s_barrier()
; template <class Epi, class Sched, bool ALIGN_EPI = false, bool SP2 = false>
; __device__ __forceinline__ void gemm_phase(PG8_LAS unsigned char* lds, const Gemm g, const Sched& S, const Epi& E, int wave_in) {
;     ...
;             PG8_LDB(B0, 0, 0); PG8_LDB(B1, 0, 1); PG8_SCHED; PG8_LDA(At, 0, 0); PG8_STAGE(PG8_SA(1, 1), a1 + hstepA, voffA);
;             PG8_WAIT_V(8); PG8_WAIT_L(0); PG8_BAR; PG8_MMA(0, 0, At, B0); PG8_MMA(0, 1, At, B1); PG8_BAR; PG8_SCHED;
;             PG8_LDA(At, 0, 1); PG8_STAGE(PG8_SB(0, 0), b2, voffB); PG8_STAGE(PG8_SB(0, 1), b2 + hstep, voffB); PG8_STAGE(PG8_SA(0, 0), a2, voffA);
;             PG8_WAIT_V(8); PG8_WAIT_L(0); PG8_BAR; PG8_MMA(1, 0, At, B0); PG8_MMA(1, 1, At, B1); PG8_BAR; PG8_SCHED;
;             PG8_LDB(B0, 1, 0); PG8_LDB(B1, 1, 1); PG8_SCHED; PG8_LDA(At, 1, 0); PG8_STAGE(PG8_SA(0, 1), a2 + hstepA, voffA);
;             PG8_WAIT_V(8); PG8_WAIT_L(0); PG8_BAR; PG8_MMA(0, 0, At, B0); PG8_MMA(0, 1, At, B1); PG8_BAR; PG8_SCHED;
;             PG8_LDA(At, 1, 1); PG8_STAGE(PG8_SB(1, 0), b3, voffB); PG8_STAGE(PG8_SB(1, 1), b3 + hstep, voffB); PG8_STAGE(PG8_SA(1, 0), a3, voffA);
;             PG8_WAIT_V(8); PG8_WAIT_L(0); PG8_BAR; PG8_MMA(1, 0, At, B0); PG8_MMA(1, 1, At, B1); PG8_BAR; PG8_SCHED;
.LBB0_43:
	s_add_u32 s50, s48, 0xfff80080
	s_addc_u32 s51, s49, -1
	s_add_i32 s72, 0, 0x10000
	s_cmp_eq_u32 s71, 28
	s_cselect_b32 s53, s43, s51
	s_cselect_b32 s52, s67, s50
	s_cselect_b32 s51, s41, s70
	s_cselect_b32 s50, s68, s69
	s_add_i32 s74, 0, 0x14000
	v_add_u32_e32 v118, s72, v214
	v_add_u32_e32 v178, s74, v214
	ds_read_b128 v[106:109], v118
	ds_read_b128 v[110:113], v118 offset:1024
	ds_read_b128 v[114:117], v118 offset:2048
	ds_read_b128 v[118:121], v118 offset:3072
	ds_read_b128 v[122:125], v178
	ds_read_b128 v[126:129], v178 offset:1024
	ds_read_b128 v[130:133], v178 offset:2048
	ds_read_b128 v[178:181], v178 offset:3072
	v_lshl_add_u64 v[238:239], s[48:49], 0, v[174:175]
	s_add_i32 m0, s58, 0xc000
	ds_read_b128 v[182:185], v217
	ds_read_b128 v[186:189], v217 offset:1024
	ds_read_b128 v[190:193], v217 offset:2048
	ds_read_b128 v[218:221], v217 offset:3072
	ds_read_b128 v[222:225], v217 offset:4096
	ds_read_b128 v[226:229], v217 offset:5120
	ds_read_b128 v[230:233], v217 offset:6144
	ds_read_b128 v[234:237], v217 offset:7168
	global_load_lds_dwordx4 v[238:239], off
	v_lshl_add_u64 v[238:239], s[48:49], 0, v[176:177]
	s_add_i32 m0, s58, 0xe000
	s_nop 0
	global_load_lds_dwordx4 v[238:239], off
	s_waitcnt vmcnt(8)
	s_waitcnt lgkmcnt(0)
	s_barrier
	s_waitcnt lgkmcnt(0)
	v_mfma_f32_16x16x32_bf16 v[154:157], v[106:109], v[182:185], v[154:157]
	v_mfma_f32_16x16x32_bf16 v[62:65], v[114:117], v[182:185], v[62:65]
	v_mfma_f32_16x16x32_bf16 v[150:153], v[106:109], v[190:193], v[150:153]
	v_mfma_f32_16x16x32_bf16 v[54:57], v[114:117], v[190:193], v[54:57]
	v_mfma_f32_16x16x32_bf16 v[142:145], v[106:109], v[222:225], v[142:145]
	v_mfma_f32_16x16x32_bf16 v[46:49], v[114:117], v[222:225], v[46:49]
	v_mfma_f32_16x16x32_bf16 v[102:105], v[106:109], v[230:233], v[102:105]
	v_mfma_f32_16x16x32_bf16 v[38:41], v[114:117], v[230:233], v[38:41]
	v_mfma_f32_16x16x32_bf16 v[154:157], v[110:113], v[186:189], v[154:157]
	v_mfma_f32_16x16x32_bf16 v[62:65], v[118:121], v[186:189], v[62:65]
	v_mfma_f32_16x16x32_bf16 v[150:153], v[110:113], v[218:221], v[150:153]
	v_mfma_f32_16x16x32_bf16 v[54:57], v[118:121], v[218:221], v[54:57]
	v_mfma_f32_16x16x32_bf16 v[142:145], v[110:113], v[226:229], v[142:145]
	v_mfma_f32_16x16x32_bf16 v[46:49], v[118:121], v[226:229], v[46:49]
	v_mfma_f32_16x16x32_bf16 v[102:105], v[110:113], v[234:237], v[102:105]
	v_mfma_f32_16x16x32_bf16 v[38:41], v[118:121], v[234:237], v[38:41]
	v_mfma_f32_16x16x32_bf16 v[134:137], v[122:125], v[182:185], v[134:137]
	v_mfma_f32_16x16x32_bf16 v[58:61], v[130:133], v[182:185], v[58:61]
	v_mfma_f32_16x16x32_bf16 v[146:149], v[122:125], v[190:193], v[146:149]
	v_mfma_f32_16x16x32_bf16 v[50:53], v[130:133], v[190:193], v[50:53]
	v_mfma_f32_16x16x32_bf16 v[138:141], v[122:125], v[222:225], v[138:141]
	v_mfma_f32_16x16x32_bf16 v[42:45], v[130:133], v[222:225], v[42:45]
	v_mfma_f32_16x16x32_bf16 v[98:101], v[122:125], v[230:233], v[98:101]
	v_mfma_f32_16x16x32_bf16 v[34:37], v[130:133], v[230:233], v[34:37]
	v_mfma_f32_16x16x32_bf16 v[134:137], v[126:129], v[186:189], v[134:137]
	v_mfma_f32_16x16x32_bf16 v[58:61], v[178:181], v[186:189], v[58:61]
	v_mfma_f32_16x16x32_bf16 v[146:149], v[126:129], v[218:221], v[146:149]
	v_mfma_f32_16x16x32_bf16 v[50:53], v[178:181], v[218:221], v[50:53]
	v_mfma_f32_16x16x32_bf16 v[138:141], v[126:129], v[226:229], v[138:141]
	v_mfma_f32_16x16x32_bf16 v[42:45], v[178:181], v[226:229], v[42:45]
	v_mfma_f32_16x16x32_bf16 v[98:101], v[126:129], v[234:237], v[98:101]
	v_mfma_f32_16x16x32_bf16 v[34:37], v[178:181], v[234:237], v[34:37]
	s_barrier
	s_add_i32 s72, s72, s57
	v_lshl_add_u64 v[238:239], s[50:51], 0, v[0:1]
	s_mov_b32 m0, s72
	ds_read_b128 v[182:185], v217 offset:16384
	ds_read_b128 v[186:189], v217 offset:17408
	ds_read_b128 v[190:193], v217 offset:18432
	ds_read_b128 v[218:221], v217 offset:19456
	ds_read_b128 v[222:225], v217 offset:20480
	ds_read_b128 v[226:229], v217 offset:21504
	ds_read_b128 v[230:233], v217 offset:22528
	ds_read_b128 v[234:237], v217 offset:23552
	global_load_lds_dwordx4 v[238:239], off
	s_add_i32 m0, s72, 0x2000
	s_add_u32 s72, s50, 0x80000
	v_lshl_add_u64 v[240:241], s[50:51], 0, v[168:169]
	s_addc_u32 s73, s51, 0
	s_add_i32 s74, s74, s57
	global_load_lds_dwordx4 v[240:241], off
	v_lshl_add_u64 v[242:243], s[72:73], 0, v[0:1]
	s_mov_b32 m0, s74
	v_lshl_add_u64 v[244:245], s[52:53], 0, v[170:171]
	global_load_lds_dwordx4 v[242:243], off
	v_lshl_add_u64 v[242:243], s[72:73], 0, v[168:169]
	s_add_i32 m0, s74, 0x2000
	s_nop 0
	global_load_lds_dwordx4 v[242:243], off
	v_lshl_add_u64 v[242:243], s[52:53], 0, v[172:173]
	s_mov_b32 m0, s58
	s_nop 0
	global_load_lds_dwordx4 v[242:243], off
	s_mov_b32 m0, s59
	s_nop 0
	global_load_lds_dwordx4 v[244:245], off
	s_waitcnt vmcnt(8)
	s_waitcnt lgkmcnt(0)
	s_barrier
; #define PG8_STAGE(bufoff, gbase, voff) do { _Pragma("unroll") for (int _i = 0; _i < 2; ++_i) \
;         __builtin_amdgcn_global_load_lds((const unsigned*)((const char*)(gbase) + (voff)[_i]), (PG8_LAS unsigned*)(lds + (bufoff) + ldsw + _i * 8192), 16, 0, 0); } while (0)
; #define PG8_LDA(dst, b, h) do { _Pragma("unroll") for (int m = 0; m < 4; ++m) _Pragma("unroll") for (int k = 0; k < 2; ++k) dst[m][k] = *(const PG8_LAS bf16x8*)(lds + PG8_SA(b, h) + aoff + m * 2048 + k * 1024); } while (0)
; #define PG8_LDB(dst, b, h) do { _Pragma("unroll") for (int n = 0; n < 2; ++n) _Pragma("unroll") for (int k = 0; k < 2; ++k) dst[n][k] = *(const PG8_LAS bf16x8*)(lds + PG8_SB(b, h) + boff + n * 2048 + k * 1024); } while (0)
; #define PG8_MMA(ai, bj, At, Bt) do { __builtin_amdgcn_s_setprio(1); _Pragma("unroll") for (int m = 0; m < 4; ++m) _Pragma("unroll") for (int n = 0; n < 2; ++n) _Pragma("unroll") for (int k = 0; k < 2; ++k) \
;         acc[ai][bj][m][n] = __builtin_amdgcn_mfma_f32_16x16x32_bf16(Bt[n][k], At[m][k], acc[ai][bj][m][n], 0, 0, 0); __builtin_amdgcn_s_setprio(0); } while (0)
; #define PG8_BAR __builtin_amdgcn_s_barrier()
; template <class Epi, class Sched, bool ALIGN_EPI = false, bool SP2 = false>
; __device__ __forceinline__ void gemm_phase(PG8_LAS unsigned char* lds, const Gemm g, const Sched& S, const Epi& E, int wave_in) {
;     ...
;             PG8_LDB(B0, 0, 0); PG8_LDB(B1, 0, 1); PG8_SCHED; PG8_LDA(At, 0, 0); PG8_STAGE(PG8_SA(1, 1), a1 + hstepA, voffA);
;             PG8_WAIT_V(8); PG8_WAIT_L(0); PG8_BAR; PG8_MMA(0, 0, At, B0); PG8_MMA(0, 1, At, B1); PG8_BAR; PG8_SCHED;
;             PG8_LDA(At, 0, 1); PG8_STAGE(PG8_SB(0, 0), b2, voffB); PG8_STAGE(PG8_SB(0, 1), b2 + hstep, voffB); PG8_STAGE(PG8_SA(0, 0), a2, voffA);
;             PG8_WAIT_V(8); PG8_WAIT_L(0); PG8_BAR; PG8_MMA(1, 0, At, B0); PG8_MMA(1, 1, At, B1); PG8_BAR; PG8_SCHED;
;             PG8_LDB(B0, 1, 0); PG8_LDB(B1, 1, 1); PG8_SCHED; PG8_LDA(At, 1, 0); PG8_STAGE(PG8_SA(0, 1), a2 + hstepA, voffA);
;             PG8_WAIT_V(8); PG8_WAIT_L(0); PG8_BAR; PG8_MMA(0, 0, At, B0); PG8_MMA(0, 1, At, B1); PG8_BAR; PG8_SCHED;
;             PG8_LDA(At, 1, 1); PG8_STAGE(PG8_SB(1, 0), b3, voffB); PG8_STAGE(PG8_SB(1, 1), b3 + hstep, voffB); PG8_STAGE(PG8_SA(1, 0), a3, voffA);
;             PG8_WAIT_V(8); PG8_WAIT_L(0); PG8_BAR; PG8_MMA(1, 0, At, B0); PG8_MMA(1, 1, At, B1); PG8_BAR; PG8_SCHED;
	s_waitcnt lgkmcnt(0)
	v_mfma_f32_16x16x32_bf16 v[94:97], v[106:109], v[182:185], v[94:97]
	v_mfma_f32_16x16x32_bf16 v[30:33], v[114:117], v[182:185], v[30:33]
	v_mfma_f32_16x16x32_bf16 v[86:89], v[106:109], v[190:193], v[86:89]
	v_mfma_f32_16x16x32_bf16 v[22:25], v[114:117], v[190:193], v[22:25]
	v_mfma_f32_16x16x32_bf16 v[78:81], v[106:109], v[222:225], v[78:81]
	v_mfma_f32_16x16x32_bf16 v[14:17], v[114:117], v[222:225], v[14:17]
	v_mfma_f32_16x16x32_bf16 v[70:73], v[106:109], v[230:233], v[70:73]
	v_mfma_f32_16x16x32_bf16 v[6:9], v[114:117], v[230:233], v[6:9]
	v_mfma_f32_16x16x32_bf16 v[94:97], v[110:113], v[186:189], v[94:97]
	v_mfma_f32_16x16x32_bf16 v[30:33], v[118:121], v[186:189], v[30:33]
	v_mfma_f32_16x16x32_bf16 v[86:89], v[110:113], v[218:221], v[86:89]
	v_mfma_f32_16x16x32_bf16 v[22:25], v[118:121], v[218:221], v[22:25]
	v_mfma_f32_16x16x32_bf16 v[78:81], v[110:113], v[226:229], v[78:81]
	v_mfma_f32_16x16x32_bf16 v[14:17], v[118:121], v[226:229], v[14:17]
	v_mfma_f32_16x16x32_bf16 v[70:73], v[110:113], v[234:237], v[70:73]
	v_mfma_f32_16x16x32_bf16 v[6:9], v[118:121], v[234:237], v[6:9]
	v_mfma_f32_16x16x32_bf16 v[90:93], v[122:125], v[182:185], v[90:93]
	v_mfma_f32_16x16x32_bf16 v[26:29], v[130:133], v[182:185], v[26:29]
	v_mfma_f32_16x16x32_bf16 v[82:85], v[122:125], v[190:193], v[82:85]
	v_mfma_f32_16x16x32_bf16 v[18:21], v[130:133], v[190:193], v[18:21]
	v_mfma_f32_16x16x32_bf16 v[74:77], v[122:125], v[222:225], v[74:77]
	v_mfma_f32_16x16x32_bf16 v[10:13], v[130:133], v[222:225], v[10:13]
	v_mfma_f32_16x16x32_bf16 v[66:69], v[122:125], v[230:233], v[66:69]
	v_mfma_f32_16x16x32_bf16 v[2:5], v[130:133], v[230:233], v[2:5]
	v_mfma_f32_16x16x32_bf16 v[90:93], v[126:129], v[186:189], v[90:93]
	v_mfma_f32_16x16x32_bf16 v[26:29], v[178:181], v[186:189], v[26:29]
	v_mfma_f32_16x16x32_bf16 v[82:85], v[126:129], v[218:221], v[82:85]
	v_mfma_f32_16x16x32_bf16 v[18:21], v[178:181], v[218:221], v[18:21]
	v_mfma_f32_16x16x32_bf16 v[74:77], v[126:129], v[226:229], v[74:77]
	v_mfma_f32_16x16x32_bf16 v[10:13], v[178:181], v[226:229], v[10:13]
	v_mfma_f32_16x16x32_bf16 v[66:69], v[126:129], v[234:237], v[66:69]
	v_mfma_f32_16x16x32_bf16 v[2:5], v[178:181], v[234:237], v[2:5]
	s_barrier
	s_add_i32 s72, 0, 0x18000
	s_add_i32 s73, 0, 0x1c000
	v_add_u32_e32 v118, s72, v214
	v_add_u32_e32 v178, s73, v214
	ds_read_b128 v[106:109], v118
	ds_read_b128 v[110:113], v118 offset:1024
	ds_read_b128 v[114:117], v118 offset:2048
	ds_read_b128 v[118:121], v118 offset:3072
	ds_read_b128 v[122:125], v178
	ds_read_b128 v[126:129], v178 offset:1024
	ds_read_b128 v[130:133], v178 offset:2048
	ds_read_b128 v[178:181], v178 offset:3072
	s_add_u32 s52, s52, 0x80000
	s_addc_u32 s53, s53, 0
	s_mov_b32 m0, s60
	v_lshl_add_u64 v[246:247], s[52:53], 0, v[172:173]
	ds_read_b128 v[182:185], v217 offset:32768
	ds_read_b128 v[186:189], v217 offset:33792
	ds_read_b128 v[190:193], v217 offset:34816
	ds_read_b128 v[218:221], v217 offset:35840
	ds_read_b128 v[222:225], v217 offset:36864
	ds_read_b128 v[226:229], v217 offset:37888
	ds_read_b128 v[230:233], v217 offset:38912
	ds_read_b128 v[234:237], v217 offset:39936
	global_load_lds_dwordx4 v[246:247], off
	v_lshl_add_u64 v[246:247], s[52:53], 0, v[170:171]
	s_mov_b32 m0, s61
	s_nop 0
	global_load_lds_dwordx4 v[246:247], off
	s_waitcnt vmcnt(8)
	s_waitcnt lgkmcnt(0)
	s_barrier
	s_waitcnt lgkmcnt(0)
	v_mfma_f32_16x16x32_bf16 v[154:157], v[106:109], v[182:185], v[154:157]
	v_mfma_f32_16x16x32_bf16 v[62:65], v[114:117], v[182:185], v[62:65]
	v_mfma_f32_16x16x32_bf16 v[150:153], v[106:109], v[190:193], v[150:153]
	v_mfma_f32_16x16x32_bf16 v[54:57], v[114:117], v[190:193], v[54:57]
	v_mfma_f32_16x16x32_bf16 v[142:145], v[106:109], v[222:225], v[142:145]
	v_mfma_f32_16x16x32_bf16 v[46:49], v[114:117], v[222:225], v[46:49]
	v_mfma_f32_16x16x32_bf16 v[102:105], v[106:109], v[230:233], v[102:105]
	v_mfma_f32_16x16x32_bf16 v[38:41], v[114:117], v[230:233], v[38:41]
	v_mfma_f32_16x16x32_bf16 v[154:157], v[110:113], v[186:189], v[154:157]
	v_mfma_f32_16x16x32_bf16 v[62:65], v[118:121], v[186:189], v[62:65]
	v_mfma_f32_16x16x32_bf16 v[150:153], v[110:113], v[218:221], v[150:153]
	v_mfma_f32_16x16x32_bf16 v[54:57], v[118:121], v[218:221], v[54:57]
	v_mfma_f32_16x16x32_bf16 v[142:145], v[110:113], v[226:229], v[142:145]
	v_mfma_f32_16x16x32_bf16 v[46:49], v[118:121], v[226:229], v[46:49]
	v_mfma_f32_16x16x32_bf16 v[102:105], v[110:113], v[234:237], v[102:105]
	v_mfma_f32_16x16x32_bf16 v[38:41], v[118:121], v[234:237], v[38:41]
	v_mfma_f32_16x16x32_bf16 v[134:137], v[122:125], v[182:185], v[134:137]
	v_mfma_f32_16x16x32_bf16 v[58:61], v[130:133], v[182:185], v[58:61]
	v_mfma_f32_16x16x32_bf16 v[146:149], v[122:125], v[190:193], v[146:149]
	v_mfma_f32_16x16x32_bf16 v[50:53], v[130:133], v[190:193], v[50:53]
	v_mfma_f32_16x16x32_bf16 v[138:141], v[122:125], v[222:225], v[138:141]
	v_mfma_f32_16x16x32_bf16 v[42:45], v[130:133], v[222:225], v[42:45]
	v_mfma_f32_16x16x32_bf16 v[98:101], v[122:125], v[230:233], v[98:101]
	v_mfma_f32_16x16x32_bf16 v[34:37], v[130:133], v[230:233], v[34:37]
	v_mfma_f32_16x16x32_bf16 v[134:137], v[126:129], v[186:189], v[134:137]
	v_mfma_f32_16x16x32_bf16 v[58:61], v[178:181], v[186:189], v[58:61]
	v_mfma_f32_16x16x32_bf16 v[146:149], v[126:129], v[218:221], v[146:149]
	v_mfma_f32_16x16x32_bf16 v[50:53], v[178:181], v[218:221], v[50:53]
	v_mfma_f32_16x16x32_bf16 v[138:141], v[126:129], v[226:229], v[138:141]
	v_mfma_f32_16x16x32_bf16 v[42:45], v[178:181], v[226:229], v[42:45]
	v_mfma_f32_16x16x32_bf16 v[98:101], v[126:129], v[234:237], v[98:101]
	v_mfma_f32_16x16x32_bf16 v[34:37], v[178:181], v[234:237], v[34:37]
	s_barrier
; #define PG8_STAGE(bufoff, gbase, voff) do { _Pragma("unroll") for (int _i = 0; _i < 2; ++_i) \
;         __builtin_amdgcn_global_load_lds((const unsigned*)((const char*)(gbase) + (voff)[_i]), (PG8_LAS unsigned*)(lds + (bufoff) + ldsw + _i * 8192), 16, 0, 0); } while (0)
; #define PG8_LDA(dst, b, h) do { _Pragma("unroll") for (int m = 0; m < 4; ++m) _Pragma("unroll") for (int k = 0; k < 2; ++k) dst[m][k] = *(const PG8_LAS bf16x8*)(lds + PG8_SA(b, h) + aoff + m * 2048 + k * 1024); } while (0)
; #define PG8_LDB(dst, b, h) do { _Pragma("unroll") for (int n = 0; n < 2; ++n) _Pragma("unroll") for (int k = 0; k < 2; ++k) dst[n][k] = *(const PG8_LAS bf16x8*)(lds + PG8_SB(b, h) + boff + n * 2048 + k * 1024); } while (0)
; #define PG8_MMA(ai, bj, At, Bt) do { __builtin_amdgcn_s_setprio(1); _Pragma("unroll") for (int m = 0; m < 4; ++m) _Pragma("unroll") for (int n = 0; n < 2; ++n) _Pragma("unroll") for (int k = 0; k < 2; ++k) \
;         acc[ai][bj][m][n] = __builtin_amdgcn_mfma_f32_16x16x32_bf16(Bt[n][k], At[m][k], acc[ai][bj][m][n], 0, 0, 0); __builtin_amdgcn_s_setprio(0); } while (0)
; #define PG8_BAR __builtin_amdgcn_s_barrier()
; template <class Epi, class Sched, bool ALIGN_EPI = false, bool SP2 = false>
; __device__ __forceinline__ void gemm_phase(PG8_LAS unsigned char* lds, const Gemm g, const Sched& S, const Epi& E, int wave_in) {
;     ...
;             PG8_LDB(B0, 0, 0); PG8_LDB(B1, 0, 1); PG8_SCHED; PG8_LDA(At, 0, 0); PG8_STAGE(PG8_SA(1, 1), a1 + hstepA, voffA);
;             PG8_WAIT_V(8); PG8_WAIT_L(0); PG8_BAR; PG8_MMA(0, 0, At, B0); PG8_MMA(0, 1, At, B1); PG8_BAR; PG8_SCHED;
;             PG8_LDA(At, 0, 1); PG8_STAGE(PG8_SB(0, 0), b2, voffB); PG8_STAGE(PG8_SB(0, 1), b2 + hstep, voffB); PG8_STAGE(PG8_SA(0, 0), a2, voffA);
;             PG8_WAIT_V(8); PG8_WAIT_L(0); PG8_BAR; PG8_MMA(1, 0, At, B0); PG8_MMA(1, 1, At, B1); PG8_BAR; PG8_SCHED;
;             PG8_LDB(B0, 1, 0); PG8_LDB(B1, 1, 1); PG8_SCHED; PG8_LDA(At, 1, 0); PG8_STAGE(PG8_SA(0, 1), a2 + hstepA, voffA);
;             PG8_WAIT_V(8); PG8_WAIT_L(0); PG8_BAR; PG8_MMA(0, 0, At, B0); PG8_MMA(0, 1, At, B1); PG8_BAR; PG8_SCHED;
;             PG8_LDA(At, 1, 1); PG8_STAGE(PG8_SB(1, 0), b3, voffB); PG8_STAGE(PG8_SB(1, 1), b3 + hstep, voffB); PG8_STAGE(PG8_SA(1, 0), a3, voffA);
;             PG8_WAIT_V(8); PG8_WAIT_L(0); PG8_BAR; PG8_MMA(1, 0, At, B0); PG8_MMA(1, 1, At, B1); PG8_BAR; PG8_SCHED;
	s_add_i32 s52, s72, s57
	v_lshl_add_u64 v[238:239], v[238:239], 0, s[84:85]
	s_mov_b32 m0, s52
	ds_read_b128 v[182:185], v217 offset:49152
	ds_read_b128 v[186:189], v217 offset:50176
	ds_read_b128 v[190:193], v217 offset:51200
	ds_read_b128 v[218:221], v217 offset:52224
	ds_read_b128 v[222:225], v217 offset:53248
	ds_read_b128 v[226:229], v217 offset:54272
	ds_read_b128 v[230:233], v217 offset:55296
	ds_read_b128 v[234:237], v217 offset:56320
	global_load_lds_dwordx4 v[238:239], off
	s_add_i32 m0, s52, 0x2000
	s_add_u32 s50, s50, 0x80080
	v_lshl_add_u64 v[238:239], v[240:241], 0, s[84:85]
	s_addc_u32 s51, s51, 0
	s_add_i32 s52, s73, s57
	global_load_lds_dwordx4 v[238:239], off
	v_lshl_add_u64 v[238:239], s[50:51], 0, v[0:1]
	s_mov_b32 m0, s52
	s_nop 0
	global_load_lds_dwordx4 v[238:239], off
	v_lshl_add_u64 v[238:239], s[50:51], 0, v[168:169]
	s_add_i32 m0, s52, 0x2000
	s_nop 0
	global_load_lds_dwordx4 v[238:239], off
	v_lshl_add_u64 v[238:239], v[242:243], 0, s[84:85]
	s_mov_b32 m0, s62
	s_nop 0
	global_load_lds_dwordx4 v[238:239], off
	v_lshl_add_u64 v[238:239], v[244:245], 0, s[84:85]
	s_mov_b32 m0, s63
	s_nop 0
	global_load_lds_dwordx4 v[238:239], off
	s_waitcnt vmcnt(8)
	s_waitcnt lgkmcnt(0)
	s_barrier
	s_waitcnt lgkmcnt(0)
	v_mfma_f32_16x16x32_bf16 v[94:97], v[106:109], v[182:185], v[94:97]
	v_mfma_f32_16x16x32_bf16 v[30:33], v[114:117], v[182:185], v[30:33]
	v_mfma_f32_16x16x32_bf16 v[86:89], v[106:109], v[190:193], v[86:89]
	v_mfma_f32_16x16x32_bf16 v[22:25], v[114:117], v[190:193], v[22:25]
	v_mfma_f32_16x16x32_bf16 v[78:81], v[106:109], v[222:225], v[78:81]
	v_mfma_f32_16x16x32_bf16 v[14:17], v[114:117], v[222:225], v[14:17]
	v_mfma_f32_16x16x32_bf16 v[70:73], v[106:109], v[230:233], v[70:73]
	v_mfma_f32_16x16x32_bf16 v[6:9], v[114:117], v[230:233], v[6:9]
	v_mfma_f32_16x16x32_bf16 v[94:97], v[110:113], v[186:189], v[94:97]
	v_mfma_f32_16x16x32_bf16 v[30:33], v[118:121], v[186:189], v[30:33]
	v_mfma_f32_16x16x32_bf16 v[86:89], v[110:113], v[218:221], v[86:89]
	v_mfma_f32_16x16x32_bf16 v[22:25], v[118:121], v[218:221], v[22:25]
	v_mfma_f32_16x16x32_bf16 v[78:81], v[110:113], v[226:229], v[78:81]
	v_mfma_f32_16x16x32_bf16 v[14:17], v[118:121], v[226:229], v[14:17]
	v_mfma_f32_16x16x32_bf16 v[70:73], v[110:113], v[234:237], v[70:73]
	v_mfma_f32_16x16x32_bf16 v[6:9], v[118:121], v[234:237], v[6:9]
	v_mfma_f32_16x16x32_bf16 v[90:93], v[122:125], v[182:185], v[90:93]
	v_mfma_f32_16x16x32_bf16 v[26:29], v[130:133], v[182:185], v[26:29]
	v_mfma_f32_16x16x32_bf16 v[82:85], v[122:125], v[190:193], v[82:85]
	v_mfma_f32_16x16x32_bf16 v[18:21], v[130:133], v[190:193], v[18:21]
	v_mfma_f32_16x16x32_bf16 v[74:77], v[122:125], v[222:225], v[74:77]
	v_mfma_f32_16x16x32_bf16 v[10:13], v[130:133], v[222:225], v[10:13]
	v_mfma_f32_16x16x32_bf16 v[66:69], v[122:125], v[230:233], v[66:69]
	v_mfma_f32_16x16x32_bf16 v[2:5], v[130:133], v[230:233], v[2:5]
	v_mfma_f32_16x16x32_bf16 v[90:93], v[126:129], v[186:189], v[90:93]
	v_mfma_f32_16x16x32_bf16 v[26:29], v[178:181], v[186:189], v[26:29]
	v_mfma_f32_16x16x32_bf16 v[82:85], v[126:129], v[218:221], v[82:85]
	v_mfma_f32_16x16x32_bf16 v[18:21], v[178:181], v[218:221], v[18:21]
	v_mfma_f32_16x16x32_bf16 v[74:77], v[126:129], v[226:229], v[74:77]
	v_mfma_f32_16x16x32_bf16 v[10:13], v[178:181], v[226:229], v[10:13]
	v_mfma_f32_16x16x32_bf16 v[66:69], v[126:129], v[234:237], v[66:69]
	v_mfma_f32_16x16x32_bf16 v[2:5], v[178:181], v[234:237], v[2:5]
	s_barrier
	s_add_i32 s71, s71, 2
	s_add_u32 s48, s48, 0x100
	s_addc_u32 s49, s49, 0
	s_add_u32 s69, s69, 0x100
	s_addc_u32 s70, s70, 0
	s_cmp_gt_u32 s71, 29
	s_cbranch_scc0 .LBB0_43
	s_and_b64 vcc, exec, s[24:25]
	s_cbranch_vccz .LBB0_46
	s_barrier

; #define PG8_STAGE(bufoff, gbase, voff) do { _Pragma("unroll") for (int _i = 0; _i < 2; ++_i) \
;         __builtin_amdgcn_global_load_lds((const unsigned*)((const char*)(gbase) + (voff)[_i]), (PG8_LAS unsigned*)(lds + (bufoff) + ldsw + _i * 8192), 16, 0, 0); } while (0)
; #define PG8_LDA(dst, b, h) do { _Pragma("unroll") for (int m = 0; m < 4; ++m) _Pragma("unroll") for (int k = 0; k < 2; ++k) dst[m][k] = *(const PG8_LAS bf16x8*)(lds + PG8_SA(b, h) + aoff + m * 2048 + k * 1024); } while (0)
; #define PG8_LDB(dst, b, h) do { _Pragma("unroll") for (int n = 0; n < 2; ++n) _Pragma("unroll") for (int k = 0; k < 2; ++k) dst[n][k] = *(const PG8_LAS bf16x8*)(lds + PG8_SB(b, h) + boff + n * 2048 + k * 1024); } while (0)
; #define PG8_MMA(ai, bj, At, Bt) do { __builtin_amdgcn_s_setprio(1); _Pragma("unroll") for (int m = 0; m < 4; ++m) _Pragma("unroll") for (int n = 0; n < 2; ++n) _Pragma("unroll") for (int k = 0; k < 2; ++k) \
;         acc[ai][bj][m][n] = __builtin_amdgcn_mfma_f32_16x16x32_bf16(Bt[n][k], At[m][k], acc[ai][bj][m][n], 0, 0, 0); __builtin_amdgcn_s_setprio(0); } while (0)
; #define PG8_BAR __builtin_amdgcn_s_barrier()
; template <class Epi, class Sched, bool ALIGN_EPI = false, bool SP2 = false>
; __device__ __forceinline__ void gemm_phase(PG8_LAS unsigned char* lds, const Gemm g, const Sched& S, const Epi& E, int wave_in) {
;     ...
;             PG8_LDB(B0, 0, 0); PG8_LDB(B1, 0, 1); PG8_SCHED; PG8_LDA(At, 0, 0); PG8_STAGE(PG8_SA(1, 1), a1 + hstepA, voffA);
;             PG8_WAIT_V(8); PG8_WAIT_L(0); PG8_BAR; PG8_MMA(0, 0, At, B0); PG8_MMA(0, 1, At, B1); PG8_BAR; PG8_SCHED;
;             PG8_LDA(At, 0, 1); PG8_STAGE(PG8_SB(0, 0), b2, voffB); PG8_STAGE(PG8_SB(0, 1), b2 + hstep, voffB); PG8_STAGE(PG8_SA(0, 0), a2, voffA);
;             PG8_WAIT_V(8); PG8_WAIT_L(0); PG8_BAR; PG8_MMA(1, 0, At, B0); PG8_MMA(1, 1, At, B1); PG8_BAR; PG8_SCHED;
;             PG8_LDB(B0, 1, 0); PG8_LDB(B1, 1, 1); PG8_SCHED; PG8_LDA(At, 1, 0); PG8_STAGE(PG8_SA(0, 1), a2 + hstepA, voffA);
;             PG8_WAIT_V(8); PG8_WAIT_L(0); PG8_BAR; PG8_MMA(0, 0, At, B0); PG8_MMA(0, 1, At, B1); PG8_BAR; PG8_SCHED;
;             PG8_LDA(At, 1, 1); PG8_STAGE(PG8_SB(1, 0), b3, voffB); PG8_STAGE(PG8_SB(1, 1), b3 + hstep, voffB); PG8_STAGE(PG8_SA(1, 0), a3, voffA);
;             PG8_WAIT_V(8); PG8_WAIT_L(0); PG8_BAR; PG8_MMA(1, 0, At, B0); PG8_MMA(1, 1, At, B1); PG8_BAR; PG8_SCHED;
.LBB0_84:
	s_add_u32 s24, s22, 0xfff80080
	s_addc_u32 s25, s23, -1
	s_add_i32 s47, 0, 0x10000
	s_cmp_eq_u32 s46, 12
	s_cselect_b32 s27, s17, s25
	s_cselect_b32 s26, s42, s24
	v_add_u32_e32 v144, s47, v147
	s_cselect_b32 s25, s11, s45
	s_cselect_b32 s24, s43, s44
	s_add_i32 s50, 0, 0x14000
	ds_read_b128 v[140:143], v144
	ds_read_b128 v[150:153], v144 offset:1024
	ds_read_b128 v[154:157], v144 offset:2048
	ds_read_b128 v[168:171], v144 offset:3072
	v_add_u32_e32 v144, s50, v147
	ds_read_b128 v[172:175], v144
	ds_read_b128 v[176:179], v144 offset:1024
	ds_read_b128 v[180:183], v144 offset:2048
	ds_read_b128 v[184:187], v144 offset:3072
	v_lshl_add_u64 v[144:145], s[22:23], 0, v[136:137]
	s_add_i32 m0, s31, 0xc000
	ds_read_b128 v[188:191], v149
	ds_read_b128 v[212:215], v149 offset:1024
	ds_read_b128 v[216:219], v149 offset:2048
	ds_read_b128 v[220:223], v149 offset:3072
	ds_read_b128 v[224:227], v149 offset:4096
	ds_read_b128 v[228:231], v149 offset:5120
	ds_read_b128 v[232:235], v149 offset:6144
	ds_read_b128 v[236:239], v149 offset:7168
	global_load_lds_dwordx4 v[144:145], off
	v_lshl_add_u64 v[144:145], s[22:23], 0, v[138:139]
	s_add_i32 m0, s31, 0xe000
	s_nop 0
	global_load_lds_dwordx4 v[144:145], off
	s_waitcnt vmcnt(8)
	s_waitcnt lgkmcnt(0)
	s_barrier
	s_waitcnt lgkmcnt(0)
	v_mfma_f32_16x16x32_bf16 v[126:129], v[140:143], v[188:191], v[126:129]
	v_mfma_f32_16x16x32_bf16 v[122:125], v[154:157], v[188:191], v[122:125]
	v_mfma_f32_16x16x32_bf16 v[118:121], v[140:143], v[216:219], v[118:121]
	v_mfma_f32_16x16x32_bf16 v[106:109], v[154:157], v[216:219], v[106:109]
	v_mfma_f32_16x16x32_bf16 v[102:105], v[140:143], v[224:227], v[102:105]
	v_mfma_f32_16x16x32_bf16 v[90:93], v[154:157], v[224:227], v[90:93]
	v_mfma_f32_16x16x32_bf16 v[86:89], v[140:143], v[232:235], v[86:89]
	v_mfma_f32_16x16x32_bf16 v[74:77], v[154:157], v[232:235], v[74:77]
	v_mfma_f32_16x16x32_bf16 v[126:129], v[150:153], v[212:215], v[126:129]
	v_mfma_f32_16x16x32_bf16 v[122:125], v[168:171], v[212:215], v[122:125]
	v_mfma_f32_16x16x32_bf16 v[118:121], v[150:153], v[220:223], v[118:121]
	v_mfma_f32_16x16x32_bf16 v[106:109], v[168:171], v[220:223], v[106:109]
	v_mfma_f32_16x16x32_bf16 v[102:105], v[150:153], v[228:231], v[102:105]
	v_mfma_f32_16x16x32_bf16 v[90:93], v[168:171], v[228:231], v[90:93]
	v_mfma_f32_16x16x32_bf16 v[86:89], v[150:153], v[236:239], v[86:89]
	v_mfma_f32_16x16x32_bf16 v[74:77], v[168:171], v[236:239], v[74:77]
	v_mfma_f32_16x16x32_bf16 v[114:117], v[172:175], v[188:191], v[114:117]
	v_mfma_f32_16x16x32_bf16 v[110:113], v[180:183], v[188:191], v[110:113]
	v_mfma_f32_16x16x32_bf16 v[98:101], v[172:175], v[216:219], v[98:101]
	v_mfma_f32_16x16x32_bf16 v[94:97], v[180:183], v[216:219], v[94:97]
	v_mfma_f32_16x16x32_bf16 v[82:85], v[172:175], v[224:227], v[82:85]
	v_mfma_f32_16x16x32_bf16 v[78:81], v[180:183], v[224:227], v[78:81]
	v_mfma_f32_16x16x32_bf16 v[70:73], v[172:175], v[232:235], v[70:73]
	v_mfma_f32_16x16x32_bf16 v[66:69], v[180:183], v[232:235], v[66:69]
	v_mfma_f32_16x16x32_bf16 v[114:117], v[176:179], v[212:215], v[114:117]
	v_mfma_f32_16x16x32_bf16 v[110:113], v[184:187], v[212:215], v[110:113]
	v_mfma_f32_16x16x32_bf16 v[98:101], v[176:179], v[220:223], v[98:101]
	v_mfma_f32_16x16x32_bf16 v[94:97], v[184:187], v[220:223], v[94:97]
	v_mfma_f32_16x16x32_bf16 v[82:85], v[176:179], v[228:231], v[82:85]
	v_mfma_f32_16x16x32_bf16 v[78:81], v[184:187], v[228:231], v[78:81]
	v_mfma_f32_16x16x32_bf16 v[70:73], v[176:179], v[236:239], v[70:73]
	v_mfma_f32_16x16x32_bf16 v[66:69], v[184:187], v[236:239], v[66:69]
	s_barrier
	s_add_i32 s47, s47, s30
	v_lshl_add_u64 v[144:145], s[24:25], 0, v[0:1]
	s_mov_b32 m0, s47
	ds_read_b128 v[188:191], v149 offset:16384
	ds_read_b128 v[212:215], v149 offset:17408
	ds_read_b128 v[216:219], v149 offset:18432
	ds_read_b128 v[220:223], v149 offset:19456
	ds_read_b128 v[224:227], v149 offset:20480
	ds_read_b128 v[228:231], v149 offset:21504
	ds_read_b128 v[232:235], v149 offset:22528
	ds_read_b128 v[236:239], v149 offset:23552
	global_load_lds_dwordx4 v[144:145], off
	s_add_i32 m0, s47, 0x2000
	s_add_u32 s48, s24, 0x40000
	v_lshl_add_u64 v[192:193], s[24:25], 0, v[130:131]
	s_addc_u32 s49, s25, 0
	s_add_i32 s47, s50, s30
	global_load_lds_dwordx4 v[192:193], off
	v_lshl_add_u64 v[240:241], s[48:49], 0, v[0:1]
	s_mov_b32 m0, s47
	v_lshl_add_u64 v[242:243], s[26:27], 0, v[132:133]
	global_load_lds_dwordx4 v[240:241], off
	v_lshl_add_u64 v[240:241], s[48:49], 0, v[130:131]
	s_add_i32 m0, s47, 0x2000
	s_nop 0
	global_load_lds_dwordx4 v[240:241], off
	v_lshl_add_u64 v[240:241], s[26:27], 0, v[134:135]
	s_mov_b32 m0, s31
	s_nop 0
	global_load_lds_dwordx4 v[240:241], off
	s_mov_b32 m0, s34
	s_nop 0
	global_load_lds_dwordx4 v[242:243], off
	s_waitcnt vmcnt(8)
	s_waitcnt lgkmcnt(0)
	s_barrier
; #define PG8_STAGE(bufoff, gbase, voff) do { _Pragma("unroll") for (int _i = 0; _i < 2; ++_i) \
;         __builtin_amdgcn_global_load_lds((const unsigned*)((const char*)(gbase) + (voff)[_i]), (PG8_LAS unsigned*)(lds + (bufoff) + ldsw + _i * 8192), 16, 0, 0); } while (0)
; #define PG8_LDA(dst, b, h) do { _Pragma("unroll") for (int m = 0; m < 4; ++m) _Pragma("unroll") for (int k = 0; k < 2; ++k) dst[m][k] = *(const PG8_LAS bf16x8*)(lds + PG8_SA(b, h) + aoff + m * 2048 + k * 1024); } while (0)
; #define PG8_LDB(dst, b, h) do { _Pragma("unroll") for (int n = 0; n < 2; ++n) _Pragma("unroll") for (int k = 0; k < 2; ++k) dst[n][k] = *(const PG8_LAS bf16x8*)(lds + PG8_SB(b, h) + boff + n * 2048 + k * 1024); } while (0)
; #define PG8_MMA(ai, bj, At, Bt) do { __builtin_amdgcn_s_setprio(1); _Pragma("unroll") for (int m = 0; m < 4; ++m) _Pragma("unroll") for (int n = 0; n < 2; ++n) _Pragma("unroll") for (int k = 0; k < 2; ++k) \
;         acc[ai][bj][m][n] = __builtin_amdgcn_mfma_f32_16x16x32_bf16(Bt[n][k], At[m][k], acc[ai][bj][m][n], 0, 0, 0); __builtin_amdgcn_s_setprio(0); } while (0)
; #define PG8_BAR __builtin_amdgcn_s_barrier()
; template <class Epi, class Sched, bool ALIGN_EPI = false, bool SP2 = false>
; __device__ __forceinline__ void gemm_phase(PG8_LAS unsigned char* lds, const Gemm g, const Sched& S, const Epi& E, int wave_in) {
;     ...
;             PG8_LDB(B0, 0, 0); PG8_LDB(B1, 0, 1); PG8_SCHED; PG8_LDA(At, 0, 0); PG8_STAGE(PG8_SA(1, 1), a1 + hstepA, voffA);
;             PG8_WAIT_V(8); PG8_WAIT_L(0); PG8_BAR; PG8_MMA(0, 0, At, B0); PG8_MMA(0, 1, At, B1); PG8_BAR; PG8_SCHED;
;             PG8_LDA(At, 0, 1); PG8_STAGE(PG8_SB(0, 0), b2, voffB); PG8_STAGE(PG8_SB(0, 1), b2 + hstep, voffB); PG8_STAGE(PG8_SA(0, 0), a2, voffA);
;             PG8_WAIT_V(8); PG8_WAIT_L(0); PG8_BAR; PG8_MMA(1, 0, At, B0); PG8_MMA(1, 1, At, B1); PG8_BAR; PG8_SCHED;
;             PG8_LDB(B0, 1, 0); PG8_LDB(B1, 1, 1); PG8_SCHED; PG8_LDA(At, 1, 0); PG8_STAGE(PG8_SA(0, 1), a2 + hstepA, voffA);
;             PG8_WAIT_V(8); PG8_WAIT_L(0); PG8_BAR; PG8_MMA(0, 0, At, B0); PG8_MMA(0, 1, At, B1); PG8_BAR; PG8_SCHED;
;             PG8_LDA(At, 1, 1); PG8_STAGE(PG8_SB(1, 0), b3, voffB); PG8_STAGE(PG8_SB(1, 1), b3 + hstep, voffB); PG8_STAGE(PG8_SA(1, 0), a3, voffA);
;             PG8_WAIT_V(8); PG8_WAIT_L(0); PG8_BAR; PG8_MMA(1, 0, At, B0); PG8_MMA(1, 1, At, B1); PG8_BAR; PG8_SCHED;
	s_waitcnt lgkmcnt(0)
	v_mfma_f32_16x16x32_bf16 v[62:65], v[140:143], v[188:191], v[62:65]
	v_mfma_f32_16x16x32_bf16 v[58:61], v[154:157], v[188:191], v[58:61]
	v_mfma_f32_16x16x32_bf16 v[54:57], v[140:143], v[216:219], v[54:57]
	v_mfma_f32_16x16x32_bf16 v[42:45], v[154:157], v[216:219], v[42:45]
	v_mfma_f32_16x16x32_bf16 v[38:41], v[140:143], v[224:227], v[38:41]
	v_mfma_f32_16x16x32_bf16 v[26:29], v[154:157], v[224:227], v[26:29]
	v_mfma_f32_16x16x32_bf16 v[22:25], v[140:143], v[232:235], v[22:25]
	v_mfma_f32_16x16x32_bf16 v[10:13], v[154:157], v[232:235], v[10:13]
	v_mfma_f32_16x16x32_bf16 v[62:65], v[150:153], v[212:215], v[62:65]
	v_mfma_f32_16x16x32_bf16 v[58:61], v[168:171], v[212:215], v[58:61]
	v_mfma_f32_16x16x32_bf16 v[54:57], v[150:153], v[220:223], v[54:57]
	v_mfma_f32_16x16x32_bf16 v[42:45], v[168:171], v[220:223], v[42:45]
	v_mfma_f32_16x16x32_bf16 v[38:41], v[150:153], v[228:231], v[38:41]
	v_mfma_f32_16x16x32_bf16 v[26:29], v[168:171], v[228:231], v[26:29]
	v_mfma_f32_16x16x32_bf16 v[22:25], v[150:153], v[236:239], v[22:25]
	v_mfma_f32_16x16x32_bf16 v[10:13], v[168:171], v[236:239], v[10:13]
	v_mfma_f32_16x16x32_bf16 v[50:53], v[172:175], v[188:191], v[50:53]
	v_mfma_f32_16x16x32_bf16 v[46:49], v[180:183], v[188:191], v[46:49]
	v_mfma_f32_16x16x32_bf16 v[34:37], v[172:175], v[216:219], v[34:37]
	v_mfma_f32_16x16x32_bf16 v[30:33], v[180:183], v[216:219], v[30:33]
	v_mfma_f32_16x16x32_bf16 v[18:21], v[172:175], v[224:227], v[18:21]
	v_mfma_f32_16x16x32_bf16 v[14:17], v[180:183], v[224:227], v[14:17]
	v_mfma_f32_16x16x32_bf16 v[6:9], v[172:175], v[232:235], v[6:9]
	v_mfma_f32_16x16x32_bf16 v[2:5], v[180:183], v[232:235], v[2:5]
	v_mfma_f32_16x16x32_bf16 v[50:53], v[176:179], v[212:215], v[50:53]
	v_mfma_f32_16x16x32_bf16 v[46:49], v[184:187], v[212:215], v[46:49]
	v_mfma_f32_16x16x32_bf16 v[34:37], v[176:179], v[220:223], v[34:37]
	v_mfma_f32_16x16x32_bf16 v[30:33], v[184:187], v[220:223], v[30:33]
	v_mfma_f32_16x16x32_bf16 v[18:21], v[176:179], v[228:231], v[18:21]
	v_mfma_f32_16x16x32_bf16 v[14:17], v[184:187], v[228:231], v[14:17]
	v_mfma_f32_16x16x32_bf16 v[6:9], v[176:179], v[236:239], v[6:9]
	v_mfma_f32_16x16x32_bf16 v[2:5], v[184:187], v[236:239], v[2:5]
	s_barrier
	s_add_i32 s47, 0, 0x18000
	s_add_i32 s48, 0, 0x1c000
	v_add_u32_e32 v168, s47, v147
	v_add_u32_e32 v184, s48, v147
	ds_read_b128 v[140:143], v168
	ds_read_b128 v[150:153], v168 offset:1024
	ds_read_b128 v[154:157], v168 offset:2048
	ds_read_b128 v[168:171], v168 offset:3072
	ds_read_b128 v[172:175], v184
	ds_read_b128 v[176:179], v184 offset:1024
	ds_read_b128 v[180:183], v184 offset:2048
	ds_read_b128 v[184:187], v184 offset:3072
	s_add_u32 s26, s26, 0x80000
	s_addc_u32 s27, s27, 0
	s_mov_b32 m0, s35
	v_lshl_add_u64 v[244:245], s[26:27], 0, v[134:135]
	ds_read_b128 v[188:191], v149 offset:32768
	ds_read_b128 v[212:215], v149 offset:33792
	ds_read_b128 v[216:219], v149 offset:34816
	ds_read_b128 v[220:223], v149 offset:35840
	ds_read_b128 v[224:227], v149 offset:36864
	ds_read_b128 v[228:231], v149 offset:37888
	ds_read_b128 v[232:235], v149 offset:38912
	ds_read_b128 v[236:239], v149 offset:39936
	global_load_lds_dwordx4 v[244:245], off
	v_lshl_add_u64 v[244:245], s[26:27], 0, v[132:133]
	s_mov_b32 m0, s36
	s_nop 0
	global_load_lds_dwordx4 v[244:245], off
	s_waitcnt vmcnt(8)
	s_waitcnt lgkmcnt(0)
	s_barrier
	s_waitcnt lgkmcnt(0)
	v_mfma_f32_16x16x32_bf16 v[126:129], v[140:143], v[188:191], v[126:129]
	v_mfma_f32_16x16x32_bf16 v[122:125], v[154:157], v[188:191], v[122:125]
	v_mfma_f32_16x16x32_bf16 v[118:121], v[140:143], v[216:219], v[118:121]
	v_mfma_f32_16x16x32_bf16 v[106:109], v[154:157], v[216:219], v[106:109]
	v_mfma_f32_16x16x32_bf16 v[102:105], v[140:143], v[224:227], v[102:105]
	v_mfma_f32_16x16x32_bf16 v[90:93], v[154:157], v[224:227], v[90:93]
	v_mfma_f32_16x16x32_bf16 v[86:89], v[140:143], v[232:235], v[86:89]
	v_mfma_f32_16x16x32_bf16 v[74:77], v[154:157], v[232:235], v[74:77]
	v_mfma_f32_16x16x32_bf16 v[126:129], v[150:153], v[212:215], v[126:129]
	v_mfma_f32_16x16x32_bf16 v[122:125], v[168:171], v[212:215], v[122:125]
	v_mfma_f32_16x16x32_bf16 v[118:121], v[150:153], v[220:223], v[118:121]
	v_mfma_f32_16x16x32_bf16 v[106:109], v[168:171], v[220:223], v[106:109]
	v_mfma_f32_16x16x32_bf16 v[102:105], v[150:153], v[228:231], v[102:105]
	v_mfma_f32_16x16x32_bf16 v[90:93], v[168:171], v[228:231], v[90:93]
	v_mfma_f32_16x16x32_bf16 v[86:89], v[150:153], v[236:239], v[86:89]
	v_mfma_f32_16x16x32_bf16 v[74:77], v[168:171], v[236:239], v[74:77]
	v_mfma_f32_16x16x32_bf16 v[114:117], v[172:175], v[188:191], v[114:117]
	v_mfma_f32_16x16x32_bf16 v[110:113], v[180:183], v[188:191], v[110:113]
	v_mfma_f32_16x16x32_bf16 v[98:101], v[172:175], v[216:219], v[98:101]
	v_mfma_f32_16x16x32_bf16 v[94:97], v[180:183], v[216:219], v[94:97]
	v_mfma_f32_16x16x32_bf16 v[82:85], v[172:175], v[224:227], v[82:85]
	v_mfma_f32_16x16x32_bf16 v[78:81], v[180:183], v[224:227], v[78:81]
	v_mfma_f32_16x16x32_bf16 v[70:73], v[172:175], v[232:235], v[70:73]
	v_mfma_f32_16x16x32_bf16 v[66:69], v[180:183], v[232:235], v[66:69]
	v_mfma_f32_16x16x32_bf16 v[114:117], v[176:179], v[212:215], v[114:117]
	v_mfma_f32_16x16x32_bf16 v[110:113], v[184:187], v[212:215], v[110:113]
	v_mfma_f32_16x16x32_bf16 v[98:101], v[176:179], v[220:223], v[98:101]
	v_mfma_f32_16x16x32_bf16 v[94:97], v[184:187], v[220:223], v[94:97]
	v_mfma_f32_16x16x32_bf16 v[82:85], v[176:179], v[228:231], v[82:85]
	v_mfma_f32_16x16x32_bf16 v[78:81], v[184:187], v[228:231], v[78:81]
	v_mfma_f32_16x16x32_bf16 v[70:73], v[176:179], v[236:239], v[70:73]
	v_mfma_f32_16x16x32_bf16 v[66:69], v[184:187], v[236:239], v[66:69]
	s_barrier
; #define PG8_STAGE(bufoff, gbase, voff) do { _Pragma("unroll") for (int _i = 0; _i < 2; ++_i) \
;         __builtin_amdgcn_global_load_lds((const unsigned*)((const char*)(gbase) + (voff)[_i]), (PG8_LAS unsigned*)(lds + (bufoff) + ldsw + _i * 8192), 16, 0, 0); } while (0)
; #define PG8_LDA(dst, b, h) do { _Pragma("unroll") for (int m = 0; m < 4; ++m) _Pragma("unroll") for (int k = 0; k < 2; ++k) dst[m][k] = *(const PG8_LAS bf16x8*)(lds + PG8_SA(b, h) + aoff + m * 2048 + k * 1024); } while (0)
; #define PG8_LDB(dst, b, h) do { _Pragma("unroll") for (int n = 0; n < 2; ++n) _Pragma("unroll") for (int k = 0; k < 2; ++k) dst[n][k] = *(const PG8_LAS bf16x8*)(lds + PG8_SB(b, h) + boff + n * 2048 + k * 1024); } while (0)
; #define PG8_MMA(ai, bj, At, Bt) do { __builtin_amdgcn_s_setprio(1); _Pragma("unroll") for (int m = 0; m < 4; ++m) _Pragma("unroll") for (int n = 0; n < 2; ++n) _Pragma("unroll") for (int k = 0; k < 2; ++k) \
;         acc[ai][bj][m][n] = __builtin_amdgcn_mfma_f32_16x16x32_bf16(Bt[n][k], At[m][k], acc[ai][bj][m][n], 0, 0, 0); __builtin_amdgcn_s_setprio(0); } while (0)
; #define PG8_BAR __builtin_amdgcn_s_barrier()
; template <class Epi, class Sched, bool ALIGN_EPI = false, bool SP2 = false>
; __device__ __forceinline__ void gemm_phase(PG8_LAS unsigned char* lds, const Gemm g, const Sched& S, const Epi& E, int wave_in) {
;     ...
;             PG8_LDB(B0, 0, 0); PG8_LDB(B1, 0, 1); PG8_SCHED; PG8_LDA(At, 0, 0); PG8_STAGE(PG8_SA(1, 1), a1 + hstepA, voffA);
;             PG8_WAIT_V(8); PG8_WAIT_L(0); PG8_BAR; PG8_MMA(0, 0, At, B0); PG8_MMA(0, 1, At, B1); PG8_BAR; PG8_SCHED;
;             PG8_LDA(At, 0, 1); PG8_STAGE(PG8_SB(0, 0), b2, voffB); PG8_STAGE(PG8_SB(0, 1), b2 + hstep, voffB); PG8_STAGE(PG8_SA(0, 0), a2, voffA);
;             PG8_WAIT_V(8); PG8_WAIT_L(0); PG8_BAR; PG8_MMA(1, 0, At, B0); PG8_MMA(1, 1, At, B1); PG8_BAR; PG8_SCHED;
;             PG8_LDB(B0, 1, 0); PG8_LDB(B1, 1, 1); PG8_SCHED; PG8_LDA(At, 1, 0); PG8_STAGE(PG8_SA(0, 1), a2 + hstepA, voffA);
;             PG8_WAIT_V(8); PG8_WAIT_L(0); PG8_BAR; PG8_MMA(0, 0, At, B0); PG8_MMA(0, 1, At, B1); PG8_BAR; PG8_SCHED;
;             PG8_LDA(At, 1, 1); PG8_STAGE(PG8_SB(1, 0), b3, voffB); PG8_STAGE(PG8_SB(1, 1), b3 + hstep, voffB); PG8_STAGE(PG8_SA(1, 0), a3, voffA);
;             PG8_WAIT_V(8); PG8_WAIT_L(0); PG8_BAR; PG8_MMA(1, 0, At, B0); PG8_MMA(1, 1, At, B1); PG8_BAR; PG8_SCHED;
	s_add_i32 s26, s47, s30
	v_lshl_add_u64 v[144:145], v[144:145], 0, s[84:85]
	s_mov_b32 m0, s26
	ds_read_b128 v[188:191], v149 offset:49152
	ds_read_b128 v[212:215], v149 offset:50176
	ds_read_b128 v[216:219], v149 offset:51200
	ds_read_b128 v[220:223], v149 offset:52224
	ds_read_b128 v[224:227], v149 offset:53248
	ds_read_b128 v[228:231], v149 offset:54272
	ds_read_b128 v[232:235], v149 offset:55296
	ds_read_b128 v[236:239], v149 offset:56320
	global_load_lds_dwordx4 v[144:145], off
	s_add_i32 m0, s26, 0x2000
	s_add_u32 s24, s24, 0x40080
	v_lshl_add_u64 v[144:145], v[192:193], 0, s[84:85]
	s_addc_u32 s25, s25, 0
	s_add_i32 s26, s48, s30
	global_load_lds_dwordx4 v[144:145], off
	v_lshl_add_u64 v[144:145], s[24:25], 0, v[0:1]
	s_mov_b32 m0, s26
	s_nop 0
	global_load_lds_dwordx4 v[144:145], off
	v_lshl_add_u64 v[144:145], s[24:25], 0, v[130:131]
	s_add_i32 m0, s26, 0x2000
	s_nop 0
	global_load_lds_dwordx4 v[144:145], off
	v_lshl_add_u64 v[144:145], v[240:241], 0, s[84:85]
	s_mov_b32 m0, s37
	s_nop 0
	global_load_lds_dwordx4 v[144:145], off
	v_lshl_add_u64 v[144:145], v[242:243], 0, s[84:85]
	s_mov_b32 m0, s38
	s_nop 0
	global_load_lds_dwordx4 v[144:145], off
	s_waitcnt vmcnt(8)
	s_waitcnt lgkmcnt(0)
	s_barrier
	s_waitcnt lgkmcnt(0)
	v_mfma_f32_16x16x32_bf16 v[62:65], v[140:143], v[188:191], v[62:65]
	v_mfma_f32_16x16x32_bf16 v[58:61], v[154:157], v[188:191], v[58:61]
	v_mfma_f32_16x16x32_bf16 v[54:57], v[140:143], v[216:219], v[54:57]
	v_mfma_f32_16x16x32_bf16 v[42:45], v[154:157], v[216:219], v[42:45]
	v_mfma_f32_16x16x32_bf16 v[38:41], v[140:143], v[224:227], v[38:41]
	v_mfma_f32_16x16x32_bf16 v[26:29], v[154:157], v[224:227], v[26:29]
	v_mfma_f32_16x16x32_bf16 v[22:25], v[140:143], v[232:235], v[22:25]
	v_mfma_f32_16x16x32_bf16 v[10:13], v[154:157], v[232:235], v[10:13]
	v_mfma_f32_16x16x32_bf16 v[62:65], v[150:153], v[212:215], v[62:65]
	v_mfma_f32_16x16x32_bf16 v[58:61], v[168:171], v[212:215], v[58:61]
	v_mfma_f32_16x16x32_bf16 v[54:57], v[150:153], v[220:223], v[54:57]
	v_mfma_f32_16x16x32_bf16 v[42:45], v[168:171], v[220:223], v[42:45]
	v_mfma_f32_16x16x32_bf16 v[38:41], v[150:153], v[228:231], v[38:41]
	v_mfma_f32_16x16x32_bf16 v[26:29], v[168:171], v[228:231], v[26:29]
	v_mfma_f32_16x16x32_bf16 v[22:25], v[150:153], v[236:239], v[22:25]
	v_mfma_f32_16x16x32_bf16 v[10:13], v[168:171], v[236:239], v[10:13]
	v_mfma_f32_16x16x32_bf16 v[50:53], v[172:175], v[188:191], v[50:53]
	v_mfma_f32_16x16x32_bf16 v[46:49], v[180:183], v[188:191], v[46:49]
	v_mfma_f32_16x16x32_bf16 v[34:37], v[172:175], v[216:219], v[34:37]
	v_mfma_f32_16x16x32_bf16 v[30:33], v[180:183], v[216:219], v[30:33]
	v_mfma_f32_16x16x32_bf16 v[18:21], v[172:175], v[224:227], v[18:21]
	v_mfma_f32_16x16x32_bf16 v[14:17], v[180:183], v[224:227], v[14:17]
	v_mfma_f32_16x16x32_bf16 v[6:9], v[172:175], v[232:235], v[6:9]
	v_mfma_f32_16x16x32_bf16 v[2:5], v[180:183], v[232:235], v[2:5]
	v_mfma_f32_16x16x32_bf16 v[50:53], v[176:179], v[212:215], v[50:53]
	v_mfma_f32_16x16x32_bf16 v[46:49], v[184:187], v[212:215], v[46:49]
	v_mfma_f32_16x16x32_bf16 v[34:37], v[176:179], v[220:223], v[34:37]
	v_mfma_f32_16x16x32_bf16 v[30:33], v[184:187], v[220:223], v[30:33]
	v_mfma_f32_16x16x32_bf16 v[18:21], v[176:179], v[228:231], v[18:21]
	v_mfma_f32_16x16x32_bf16 v[14:17], v[184:187], v[228:231], v[14:17]
	v_mfma_f32_16x16x32_bf16 v[6:9], v[176:179], v[236:239], v[6:9]
	v_mfma_f32_16x16x32_bf16 v[2:5], v[184:187], v[236:239], v[2:5]
	s_barrier
	s_add_i32 s46, s46, 2
	s_add_u32 s22, s22, 0x100
	s_addc_u32 s23, s23, 0
	s_add_u32 s44, s44, 0x100
	s_addc_u32 s45, s45, 0
	s_cmp_gt_u32 s46, 13
	s_cbranch_scc0 .LBB0_84
	s_and_b64 vcc, exec, s[8:9]
	v_readlane_b32 s26, v254, 6
	v_readlane_b32 s27, v254, 7
	s_cbranch_vccz .LBB0_87
	s_barrier

; #define PG8_STAGE(bufoff, gbase, voff) do { _Pragma("unroll") for (int _i = 0; _i < 2; ++_i) \
;         __builtin_amdgcn_global_load_lds((const unsigned*)((const char*)(gbase) + (voff)[_i]), (PG8_LAS unsigned*)(lds + (bufoff) + ldsw + _i * 8192), 16, 0, 0); } while (0)
; #define PG8_LDA(dst, b, h) do { _Pragma("unroll") for (int m = 0; m < 4; ++m) _Pragma("unroll") for (int k = 0; k < 2; ++k) dst[m][k] = *(const PG8_LAS bf16x8*)(lds + PG8_SA(b, h) + aoff + m * 2048 + k * 1024); } while (0)
; #define PG8_LDB(dst, b, h) do { _Pragma("unroll") for (int n = 0; n < 2; ++n) _Pragma("unroll") for (int k = 0; k < 2; ++k) dst[n][k] = *(const PG8_LAS bf16x8*)(lds + PG8_SB(b, h) + boff + n * 2048 + k * 1024); } while (0)
; #define PG8_MMA(ai, bj, At, Bt) do { __builtin_amdgcn_s_setprio(1); _Pragma("unroll") for (int m = 0; m < 4; ++m) _Pragma("unroll") for (int n = 0; n < 2; ++n) _Pragma("unroll") for (int k = 0; k < 2; ++k) \
;         acc[ai][bj][m][n] = __builtin_amdgcn_mfma_f32_16x16x32_bf16(Bt[n][k], At[m][k], acc[ai][bj][m][n], 0, 0, 0); __builtin_amdgcn_s_setprio(0); } while (0)
; #define PG8_BAR __builtin_amdgcn_s_barrier()
; template <class Epi, class Sched, bool ALIGN_EPI = false, bool SP2 = false>
; __device__ __forceinline__ void gemm_phase(PG8_LAS unsigned char* lds, const Gemm g, const Sched& S, const Epi& E, int wave_in) {
;     ...
;             PG8_LDB(B0, 0, 0); PG8_LDB(B1, 0, 1); PG8_SCHED; PG8_LDA(At, 0, 0); PG8_STAGE(PG8_SA(1, 1), a1 + hstepA, voffA);
;             PG8_WAIT_V(8); PG8_WAIT_L(0); PG8_BAR; PG8_MMA(0, 0, At, B0); PG8_MMA(0, 1, At, B1); PG8_BAR; PG8_SCHED;
;             PG8_LDA(At, 0, 1); PG8_STAGE(PG8_SB(0, 0), b2, voffB); PG8_STAGE(PG8_SB(0, 1), b2 + hstep, voffB); PG8_STAGE(PG8_SA(0, 0), a2, voffA);
;             PG8_WAIT_V(8); PG8_WAIT_L(0); PG8_BAR; PG8_MMA(1, 0, At, B0); PG8_MMA(1, 1, At, B1); PG8_BAR; PG8_SCHED;
;             PG8_LDB(B0, 1, 0); PG8_LDB(B1, 1, 1); PG8_SCHED; PG8_LDA(At, 1, 0); PG8_STAGE(PG8_SA(0, 1), a2 + hstepA, voffA);
;             PG8_WAIT_V(8); PG8_WAIT_L(0); PG8_BAR; PG8_MMA(0, 0, At, B0); PG8_MMA(0, 1, At, B1); PG8_BAR; PG8_SCHED;
;             PG8_LDA(At, 1, 1); PG8_STAGE(PG8_SB(1, 0), b3, voffB); PG8_STAGE(PG8_SB(1, 1), b3 + hstep, voffB); PG8_STAGE(PG8_SA(1, 0), a3, voffA);
;             PG8_WAIT_V(8); PG8_WAIT_L(0); PG8_BAR; PG8_MMA(1, 0, At, B0); PG8_MMA(1, 1, At, B1); PG8_BAR; PG8_SCHED;
.LBB0_107:
	s_add_u32 s28, s26, 0xfff80080
	s_addc_u32 s29, s27, -1
	s_add_i32 s55, 0, 0x10000
	s_cmp_eq_u32 s54, 4
	s_cselect_b32 s31, s21, s29
	s_cselect_b32 s30, s50, s28
	v_add_u32_e32 v144, s55, v147
	s_cselect_b32 s29, s19, s53
	s_cselect_b32 s28, s51, s52
	s_add_i32 s58, 0, 0x14000
	ds_read_b128 v[140:143], v144
	ds_read_b128 v[150:153], v144 offset:1024
	ds_read_b128 v[154:157], v144 offset:2048
	ds_read_b128 v[168:171], v144 offset:3072
	v_add_u32_e32 v144, s58, v147
	ds_read_b128 v[172:175], v144
	ds_read_b128 v[176:179], v144 offset:1024
	ds_read_b128 v[180:183], v144 offset:2048
	ds_read_b128 v[184:187], v144 offset:3072
	v_lshl_add_u64 v[144:145], s[26:27], 0, v[136:137]
	s_add_i32 m0, s41, 0xc000
	ds_read_b128 v[188:191], v149
	ds_read_b128 v[212:215], v149 offset:1024
	ds_read_b128 v[216:219], v149 offset:2048
	ds_read_b128 v[220:223], v149 offset:3072
	ds_read_b128 v[224:227], v149 offset:4096
	ds_read_b128 v[228:231], v149 offset:5120
	ds_read_b128 v[232:235], v149 offset:6144
	ds_read_b128 v[236:239], v149 offset:7168
	global_load_lds_dwordx4 v[144:145], off
	v_lshl_add_u64 v[144:145], s[26:27], 0, v[138:139]
	s_add_i32 m0, s41, 0xe000
	s_nop 0
	global_load_lds_dwordx4 v[144:145], off
	s_waitcnt vmcnt(8)
	s_waitcnt lgkmcnt(0)
	s_barrier
	s_waitcnt lgkmcnt(0)
	v_mfma_f32_16x16x32_bf16 v[126:129], v[140:143], v[188:191], v[126:129]
	v_mfma_f32_16x16x32_bf16 v[122:125], v[154:157], v[188:191], v[122:125]
	v_mfma_f32_16x16x32_bf16 v[110:113], v[140:143], v[216:219], v[110:113]
	v_mfma_f32_16x16x32_bf16 v[106:109], v[154:157], v[216:219], v[106:109]
	v_mfma_f32_16x16x32_bf16 v[94:97], v[140:143], v[224:227], v[94:97]
	v_mfma_f32_16x16x32_bf16 v[90:93], v[154:157], v[224:227], v[90:93]
	v_mfma_f32_16x16x32_bf16 v[78:81], v[140:143], v[232:235], v[78:81]
	v_mfma_f32_16x16x32_bf16 v[74:77], v[154:157], v[232:235], v[74:77]
	v_mfma_f32_16x16x32_bf16 v[126:129], v[150:153], v[212:215], v[126:129]
	v_mfma_f32_16x16x32_bf16 v[122:125], v[168:171], v[212:215], v[122:125]
	v_mfma_f32_16x16x32_bf16 v[110:113], v[150:153], v[220:223], v[110:113]
	v_mfma_f32_16x16x32_bf16 v[106:109], v[168:171], v[220:223], v[106:109]
	v_mfma_f32_16x16x32_bf16 v[94:97], v[150:153], v[228:231], v[94:97]
	v_mfma_f32_16x16x32_bf16 v[90:93], v[168:171], v[228:231], v[90:93]
	v_mfma_f32_16x16x32_bf16 v[78:81], v[150:153], v[236:239], v[78:81]
	v_mfma_f32_16x16x32_bf16 v[74:77], v[168:171], v[236:239], v[74:77]
	v_mfma_f32_16x16x32_bf16 v[118:121], v[172:175], v[188:191], v[118:121]
	v_mfma_f32_16x16x32_bf16 v[114:117], v[180:183], v[188:191], v[114:117]
	v_mfma_f32_16x16x32_bf16 v[102:105], v[172:175], v[216:219], v[102:105]
	v_mfma_f32_16x16x32_bf16 v[98:101], v[180:183], v[216:219], v[98:101]
	v_mfma_f32_16x16x32_bf16 v[86:89], v[172:175], v[224:227], v[86:89]
	v_mfma_f32_16x16x32_bf16 v[82:85], v[180:183], v[224:227], v[82:85]
	v_mfma_f32_16x16x32_bf16 v[70:73], v[172:175], v[232:235], v[70:73]
	v_mfma_f32_16x16x32_bf16 v[66:69], v[180:183], v[232:235], v[66:69]
	v_mfma_f32_16x16x32_bf16 v[118:121], v[176:179], v[212:215], v[118:121]
	v_mfma_f32_16x16x32_bf16 v[114:117], v[184:187], v[212:215], v[114:117]
	v_mfma_f32_16x16x32_bf16 v[102:105], v[176:179], v[220:223], v[102:105]
	v_mfma_f32_16x16x32_bf16 v[98:101], v[184:187], v[220:223], v[98:101]
	v_mfma_f32_16x16x32_bf16 v[86:89], v[176:179], v[228:231], v[86:89]
	v_mfma_f32_16x16x32_bf16 v[82:85], v[184:187], v[228:231], v[82:85]
	v_mfma_f32_16x16x32_bf16 v[70:73], v[176:179], v[236:239], v[70:73]
	v_mfma_f32_16x16x32_bf16 v[66:69], v[184:187], v[236:239], v[66:69]
	s_barrier
	s_add_i32 s55, s55, s40
	v_lshl_add_u64 v[144:145], s[28:29], 0, v[0:1]
	s_mov_b32 m0, s55
	ds_read_b128 v[188:191], v149 offset:16384
	ds_read_b128 v[212:215], v149 offset:17408
	ds_read_b128 v[216:219], v149 offset:18432
	ds_read_b128 v[220:223], v149 offset:19456
	ds_read_b128 v[224:227], v149 offset:20480
	ds_read_b128 v[228:231], v149 offset:21504
	ds_read_b128 v[232:235], v149 offset:22528
	ds_read_b128 v[236:239], v149 offset:23552
	global_load_lds_dwordx4 v[144:145], off
	s_add_i32 m0, s55, 0x2000
	s_add_u32 s56, s28, 0x20000
	v_lshl_add_u64 v[192:193], s[28:29], 0, v[130:131]
	s_addc_u32 s57, s29, 0
	s_add_i32 s55, s58, s40
	global_load_lds_dwordx4 v[192:193], off
	v_lshl_add_u64 v[240:241], s[56:57], 0, v[0:1]
	s_mov_b32 m0, s55
	v_lshl_add_u64 v[242:243], s[30:31], 0, v[132:133]
	global_load_lds_dwordx4 v[240:241], off
	v_lshl_add_u64 v[240:241], s[56:57], 0, v[130:131]
	s_add_i32 m0, s55, 0x2000
	s_nop 0
	global_load_lds_dwordx4 v[240:241], off
	v_lshl_add_u64 v[240:241], s[30:31], 0, v[134:135]
	s_mov_b32 m0, s41
	s_nop 0
	global_load_lds_dwordx4 v[240:241], off
	s_mov_b32 m0, s42
	s_nop 0
	global_load_lds_dwordx4 v[242:243], off
	s_waitcnt vmcnt(8)
	s_waitcnt lgkmcnt(0)
	s_barrier
; #define PG8_STAGE(bufoff, gbase, voff) do { _Pragma("unroll") for (int _i = 0; _i < 2; ++_i) \
;         __builtin_amdgcn_global_load_lds((const unsigned*)((const char*)(gbase) + (voff)[_i]), (PG8_LAS unsigned*)(lds + (bufoff) + ldsw + _i * 8192), 16, 0, 0); } while (0)
; #define PG8_LDA(dst, b, h) do { _Pragma("unroll") for (int m = 0; m < 4; ++m) _Pragma("unroll") for (int k = 0; k < 2; ++k) dst[m][k] = *(const PG8_LAS bf16x8*)(lds + PG8_SA(b, h) + aoff + m * 2048 + k * 1024); } while (0)
; #define PG8_LDB(dst, b, h) do { _Pragma("unroll") for (int n = 0; n < 2; ++n) _Pragma("unroll") for (int k = 0; k < 2; ++k) dst[n][k] = *(const PG8_LAS bf16x8*)(lds + PG8_SB(b, h) + boff + n * 2048 + k * 1024); } while (0)
; #define PG8_MMA(ai, bj, At, Bt) do { __builtin_amdgcn_s_setprio(1); _Pragma("unroll") for (int m = 0; m < 4; ++m) _Pragma("unroll") for (int n = 0; n < 2; ++n) _Pragma("unroll") for (int k = 0; k < 2; ++k) \
;         acc[ai][bj][m][n] = __builtin_amdgcn_mfma_f32_16x16x32_bf16(Bt[n][k], At[m][k], acc[ai][bj][m][n], 0, 0, 0); __builtin_amdgcn_s_setprio(0); } while (0)
; #define PG8_BAR __builtin_amdgcn_s_barrier()
; template <class Epi, class Sched, bool ALIGN_EPI = false, bool SP2 = false>
; __device__ __forceinline__ void gemm_phase(PG8_LAS unsigned char* lds, const Gemm g, const Sched& S, const Epi& E, int wave_in) {
;     ...
;             PG8_LDB(B0, 0, 0); PG8_LDB(B1, 0, 1); PG8_SCHED; PG8_LDA(At, 0, 0); PG8_STAGE(PG8_SA(1, 1), a1 + hstepA, voffA);
;             PG8_WAIT_V(8); PG8_WAIT_L(0); PG8_BAR; PG8_MMA(0, 0, At, B0); PG8_MMA(0, 1, At, B1); PG8_BAR; PG8_SCHED;
;             PG8_LDA(At, 0, 1); PG8_STAGE(PG8_SB(0, 0), b2, voffB); PG8_STAGE(PG8_SB(0, 1), b2 + hstep, voffB); PG8_STAGE(PG8_SA(0, 0), a2, voffA);
;             PG8_WAIT_V(8); PG8_WAIT_L(0); PG8_BAR; PG8_MMA(1, 0, At, B0); PG8_MMA(1, 1, At, B1); PG8_BAR; PG8_SCHED;
;             PG8_LDB(B0, 1, 0); PG8_LDB(B1, 1, 1); PG8_SCHED; PG8_LDA(At, 1, 0); PG8_STAGE(PG8_SA(0, 1), a2 + hstepA, voffA);
;             PG8_WAIT_V(8); PG8_WAIT_L(0); PG8_BAR; PG8_MMA(0, 0, At, B0); PG8_MMA(0, 1, At, B1); PG8_BAR; PG8_SCHED;
;             PG8_LDA(At, 1, 1); PG8_STAGE(PG8_SB(1, 0), b3, voffB); PG8_STAGE(PG8_SB(1, 1), b3 + hstep, voffB); PG8_STAGE(PG8_SA(1, 0), a3, voffA);
;             PG8_WAIT_V(8); PG8_WAIT_L(0); PG8_BAR; PG8_MMA(1, 0, At, B0); PG8_MMA(1, 1, At, B1); PG8_BAR; PG8_SCHED;
	s_waitcnt lgkmcnt(0)
	v_mfma_f32_16x16x32_bf16 v[62:65], v[140:143], v[188:191], v[62:65]
	v_mfma_f32_16x16x32_bf16 v[58:61], v[154:157], v[188:191], v[58:61]
	v_mfma_f32_16x16x32_bf16 v[46:49], v[140:143], v[216:219], v[46:49]
	v_mfma_f32_16x16x32_bf16 v[42:45], v[154:157], v[216:219], v[42:45]
	v_mfma_f32_16x16x32_bf16 v[30:33], v[140:143], v[224:227], v[30:33]
	v_mfma_f32_16x16x32_bf16 v[26:29], v[154:157], v[224:227], v[26:29]
	v_mfma_f32_16x16x32_bf16 v[14:17], v[140:143], v[232:235], v[14:17]
	v_mfma_f32_16x16x32_bf16 v[10:13], v[154:157], v[232:235], v[10:13]
	v_mfma_f32_16x16x32_bf16 v[62:65], v[150:153], v[212:215], v[62:65]
	v_mfma_f32_16x16x32_bf16 v[58:61], v[168:171], v[212:215], v[58:61]
	v_mfma_f32_16x16x32_bf16 v[46:49], v[150:153], v[220:223], v[46:49]
	v_mfma_f32_16x16x32_bf16 v[42:45], v[168:171], v[220:223], v[42:45]
	v_mfma_f32_16x16x32_bf16 v[30:33], v[150:153], v[228:231], v[30:33]
	v_mfma_f32_16x16x32_bf16 v[26:29], v[168:171], v[228:231], v[26:29]
	v_mfma_f32_16x16x32_bf16 v[14:17], v[150:153], v[236:239], v[14:17]
	v_mfma_f32_16x16x32_bf16 v[10:13], v[168:171], v[236:239], v[10:13]
	v_mfma_f32_16x16x32_bf16 v[54:57], v[172:175], v[188:191], v[54:57]
	v_mfma_f32_16x16x32_bf16 v[50:53], v[180:183], v[188:191], v[50:53]
	v_mfma_f32_16x16x32_bf16 v[38:41], v[172:175], v[216:219], v[38:41]
	v_mfma_f32_16x16x32_bf16 v[34:37], v[180:183], v[216:219], v[34:37]
	v_mfma_f32_16x16x32_bf16 v[22:25], v[172:175], v[224:227], v[22:25]
	v_mfma_f32_16x16x32_bf16 v[18:21], v[180:183], v[224:227], v[18:21]
	v_mfma_f32_16x16x32_bf16 v[6:9], v[172:175], v[232:235], v[6:9]
	v_mfma_f32_16x16x32_bf16 v[2:5], v[180:183], v[232:235], v[2:5]
	v_mfma_f32_16x16x32_bf16 v[54:57], v[176:179], v[212:215], v[54:57]
	v_mfma_f32_16x16x32_bf16 v[50:53], v[184:187], v[212:215], v[50:53]
	v_mfma_f32_16x16x32_bf16 v[38:41], v[176:179], v[220:223], v[38:41]
	v_mfma_f32_16x16x32_bf16 v[34:37], v[184:187], v[220:223], v[34:37]
	v_mfma_f32_16x16x32_bf16 v[22:25], v[176:179], v[228:231], v[22:25]
	v_mfma_f32_16x16x32_bf16 v[18:21], v[184:187], v[228:231], v[18:21]
	v_mfma_f32_16x16x32_bf16 v[6:9], v[176:179], v[236:239], v[6:9]
	v_mfma_f32_16x16x32_bf16 v[2:5], v[184:187], v[236:239], v[2:5]
	s_barrier
	s_add_i32 s55, 0, 0x18000
	s_add_i32 s56, 0, 0x1c000
	v_add_u32_e32 v168, s55, v147
	v_add_u32_e32 v184, s56, v147
	ds_read_b128 v[140:143], v168
	ds_read_b128 v[150:153], v168 offset:1024
	ds_read_b128 v[154:157], v168 offset:2048
	ds_read_b128 v[168:171], v168 offset:3072
	ds_read_b128 v[172:175], v184
	ds_read_b128 v[176:179], v184 offset:1024
	ds_read_b128 v[180:183], v184 offset:2048
	ds_read_b128 v[184:187], v184 offset:3072
	s_add_u32 s30, s30, 0x80000
	s_addc_u32 s31, s31, 0
	s_mov_b32 m0, s43
	v_lshl_add_u64 v[244:245], s[30:31], 0, v[134:135]
	ds_read_b128 v[188:191], v149 offset:32768
	ds_read_b128 v[212:215], v149 offset:33792
	ds_read_b128 v[216:219], v149 offset:34816
	ds_read_b128 v[220:223], v149 offset:35840
	ds_read_b128 v[224:227], v149 offset:36864
	ds_read_b128 v[228:231], v149 offset:37888
	ds_read_b128 v[232:235], v149 offset:38912
	ds_read_b128 v[236:239], v149 offset:39936
	global_load_lds_dwordx4 v[244:245], off
	v_lshl_add_u64 v[244:245], s[30:31], 0, v[132:133]
	s_mov_b32 m0, s44
	s_nop 0
	global_load_lds_dwordx4 v[244:245], off
	s_waitcnt vmcnt(8)
	s_waitcnt lgkmcnt(0)
	s_barrier
	s_waitcnt lgkmcnt(0)
	v_mfma_f32_16x16x32_bf16 v[126:129], v[140:143], v[188:191], v[126:129]
	v_mfma_f32_16x16x32_bf16 v[122:125], v[154:157], v[188:191], v[122:125]
	v_mfma_f32_16x16x32_bf16 v[110:113], v[140:143], v[216:219], v[110:113]
	v_mfma_f32_16x16x32_bf16 v[106:109], v[154:157], v[216:219], v[106:109]
	v_mfma_f32_16x16x32_bf16 v[94:97], v[140:143], v[224:227], v[94:97]
	v_mfma_f32_16x16x32_bf16 v[90:93], v[154:157], v[224:227], v[90:93]
	v_mfma_f32_16x16x32_bf16 v[78:81], v[140:143], v[232:235], v[78:81]
	v_mfma_f32_16x16x32_bf16 v[74:77], v[154:157], v[232:235], v[74:77]
	v_mfma_f32_16x16x32_bf16 v[126:129], v[150:153], v[212:215], v[126:129]
	v_mfma_f32_16x16x32_bf16 v[122:125], v[168:171], v[212:215], v[122:125]
	v_mfma_f32_16x16x32_bf16 v[110:113], v[150:153], v[220:223], v[110:113]
	v_mfma_f32_16x16x32_bf16 v[106:109], v[168:171], v[220:223], v[106:109]
	v_mfma_f32_16x16x32_bf16 v[94:97], v[150:153], v[228:231], v[94:97]
	v_mfma_f32_16x16x32_bf16 v[90:93], v[168:171], v[228:231], v[90:93]
	v_mfma_f32_16x16x32_bf16 v[78:81], v[150:153], v[236:239], v[78:81]
	v_mfma_f32_16x16x32_bf16 v[74:77], v[168:171], v[236:239], v[74:77]
	v_mfma_f32_16x16x32_bf16 v[118:121], v[172:175], v[188:191], v[118:121]
	v_mfma_f32_16x16x32_bf16 v[114:117], v[180:183], v[188:191], v[114:117]
	v_mfma_f32_16x16x32_bf16 v[102:105], v[172:175], v[216:219], v[102:105]
	v_mfma_f32_16x16x32_bf16 v[98:101], v[180:183], v[216:219], v[98:101]
	v_mfma_f32_16x16x32_bf16 v[86:89], v[172:175], v[224:227], v[86:89]
	v_mfma_f32_16x16x32_bf16 v[82:85], v[180:183], v[224:227], v[82:85]
	v_mfma_f32_16x16x32_bf16 v[70:73], v[172:175], v[232:235], v[70:73]
	v_mfma_f32_16x16x32_bf16 v[66:69], v[180:183], v[232:235], v[66:69]
	v_mfma_f32_16x16x32_bf16 v[118:121], v[176:179], v[212:215], v[118:121]
	v_mfma_f32_16x16x32_bf16 v[114:117], v[184:187], v[212:215], v[114:117]
	v_mfma_f32_16x16x32_bf16 v[102:105], v[176:179], v[220:223], v[102:105]
	v_mfma_f32_16x16x32_bf16 v[98:101], v[184:187], v[220:223], v[98:101]
	v_mfma_f32_16x16x32_bf16 v[86:89], v[176:179], v[228:231], v[86:89]
	v_mfma_f32_16x16x32_bf16 v[82:85], v[184:187], v[228:231], v[82:85]
	v_mfma_f32_16x16x32_bf16 v[70:73], v[176:179], v[236:239], v[70:73]
	v_mfma_f32_16x16x32_bf16 v[66:69], v[184:187], v[236:239], v[66:69]
	s_barrier
; #define PG8_STAGE(bufoff, gbase, voff) do { _Pragma("unroll") for (int _i = 0; _i < 2; ++_i) \
;         __builtin_amdgcn_global_load_lds((const unsigned*)((const char*)(gbase) + (voff)[_i]), (PG8_LAS unsigned*)(lds + (bufoff) + ldsw + _i * 8192), 16, 0, 0); } while (0)
; #define PG8_LDA(dst, b, h) do { _Pragma("unroll") for (int m = 0; m < 4; ++m) _Pragma("unroll") for (int k = 0; k < 2; ++k) dst[m][k] = *(const PG8_LAS bf16x8*)(lds + PG8_SA(b, h) + aoff + m * 2048 + k * 1024); } while (0)
; #define PG8_LDB(dst, b, h) do { _Pragma("unroll") for (int n = 0; n < 2; ++n) _Pragma("unroll") for (int k = 0; k < 2; ++k) dst[n][k] = *(const PG8_LAS bf16x8*)(lds + PG8_SB(b, h) + boff + n * 2048 + k * 1024); } while (0)
; #define PG8_MMA(ai, bj, At, Bt) do { __builtin_amdgcn_s_setprio(1); _Pragma("unroll") for (int m = 0; m < 4; ++m) _Pragma("unroll") for (int n = 0; n < 2; ++n) _Pragma("unroll") for (int k = 0; k < 2; ++k) \
;         acc[ai][bj][m][n] = __builtin_amdgcn_mfma_f32_16x16x32_bf16(Bt[n][k], At[m][k], acc[ai][bj][m][n], 0, 0, 0); __builtin_amdgcn_s_setprio(0); } while (0)
; #define PG8_BAR __builtin_amdgcn_s_barrier()
; template <class Epi, class Sched, bool ALIGN_EPI = false, bool SP2 = false>
; __device__ __forceinline__ void gemm_phase(PG8_LAS unsigned char* lds, const Gemm g, const Sched& S, const Epi& E, int wave_in) {
;     ...
;             PG8_LDB(B0, 0, 0); PG8_LDB(B1, 0, 1); PG8_SCHED; PG8_LDA(At, 0, 0); PG8_STAGE(PG8_SA(1, 1), a1 + hstepA, voffA);
;             PG8_WAIT_V(8); PG8_WAIT_L(0); PG8_BAR; PG8_MMA(0, 0, At, B0); PG8_MMA(0, 1, At, B1); PG8_BAR; PG8_SCHED;
;             PG8_LDA(At, 0, 1); PG8_STAGE(PG8_SB(0, 0), b2, voffB); PG8_STAGE(PG8_SB(0, 1), b2 + hstep, voffB); PG8_STAGE(PG8_SA(0, 0), a2, voffA);
;             PG8_WAIT_V(8); PG8_WAIT_L(0); PG8_BAR; PG8_MMA(1, 0, At, B0); PG8_MMA(1, 1, At, B1); PG8_BAR; PG8_SCHED;
;             PG8_LDB(B0, 1, 0); PG8_LDB(B1, 1, 1); PG8_SCHED; PG8_LDA(At, 1, 0); PG8_STAGE(PG8_SA(0, 1), a2 + hstepA, voffA);
;             PG8_WAIT_V(8); PG8_WAIT_L(0); PG8_BAR; PG8_MMA(0, 0, At, B0); PG8_MMA(0, 1, At, B1); PG8_BAR; PG8_SCHED;
;             PG8_LDA(At, 1, 1); PG8_STAGE(PG8_SB(1, 0), b3, voffB); PG8_STAGE(PG8_SB(1, 1), b3 + hstep, voffB); PG8_STAGE(PG8_SA(1, 0), a3, voffA);
;             PG8_WAIT_V(8); PG8_WAIT_L(0); PG8_BAR; PG8_MMA(1, 0, At, B0); PG8_MMA(1, 1, At, B1); PG8_BAR; PG8_SCHED;
	s_add_i32 s30, s55, s40
	v_lshl_add_u64 v[144:145], v[144:145], 0, s[84:85]
	s_mov_b32 m0, s30
	ds_read_b128 v[188:191], v149 offset:49152
	ds_read_b128 v[212:215], v149 offset:50176
	ds_read_b128 v[216:219], v149 offset:51200
	ds_read_b128 v[220:223], v149 offset:52224
	ds_read_b128 v[224:227], v149 offset:53248
	ds_read_b128 v[228:231], v149 offset:54272
	ds_read_b128 v[232:235], v149 offset:55296
	ds_read_b128 v[236:239], v149 offset:56320
	global_load_lds_dwordx4 v[144:145], off
	s_add_i32 m0, s30, 0x2000
	s_add_u32 s28, s28, 0x20080
	v_lshl_add_u64 v[144:145], v[192:193], 0, s[84:85]
	s_addc_u32 s29, s29, 0
	s_add_i32 s30, s56, s40
	global_load_lds_dwordx4 v[144:145], off
	v_lshl_add_u64 v[144:145], s[28:29], 0, v[0:1]
	s_mov_b32 m0, s30
	s_nop 0
	global_load_lds_dwordx4 v[144:145], off
	v_lshl_add_u64 v[144:145], s[28:29], 0, v[130:131]
	s_add_i32 m0, s30, 0x2000
	s_nop 0
	global_load_lds_dwordx4 v[144:145], off
	v_lshl_add_u64 v[144:145], v[240:241], 0, s[84:85]
	s_mov_b32 m0, s45
	s_nop 0
	global_load_lds_dwordx4 v[144:145], off
	v_lshl_add_u64 v[144:145], v[242:243], 0, s[84:85]
	s_mov_b32 m0, s46
	s_nop 0
	global_load_lds_dwordx4 v[144:145], off
	s_waitcnt vmcnt(8)
	s_waitcnt lgkmcnt(0)
	s_barrier
	s_waitcnt lgkmcnt(0)
	v_mfma_f32_16x16x32_bf16 v[62:65], v[140:143], v[188:191], v[62:65]
	v_mfma_f32_16x16x32_bf16 v[58:61], v[154:157], v[188:191], v[58:61]
	v_mfma_f32_16x16x32_bf16 v[46:49], v[140:143], v[216:219], v[46:49]
	v_mfma_f32_16x16x32_bf16 v[42:45], v[154:157], v[216:219], v[42:45]
	v_mfma_f32_16x16x32_bf16 v[30:33], v[140:143], v[224:227], v[30:33]
	v_mfma_f32_16x16x32_bf16 v[26:29], v[154:157], v[224:227], v[26:29]
	v_mfma_f32_16x16x32_bf16 v[14:17], v[140:143], v[232:235], v[14:17]
	v_mfma_f32_16x16x32_bf16 v[10:13], v[154:157], v[232:235], v[10:13]
	v_mfma_f32_16x16x32_bf16 v[62:65], v[150:153], v[212:215], v[62:65]
	v_mfma_f32_16x16x32_bf16 v[58:61], v[168:171], v[212:215], v[58:61]
	v_mfma_f32_16x16x32_bf16 v[46:49], v[150:153], v[220:223], v[46:49]
	v_mfma_f32_16x16x32_bf16 v[42:45], v[168:171], v[220:223], v[42:45]
	v_mfma_f32_16x16x32_bf16 v[30:33], v[150:153], v[228:231], v[30:33]
	v_mfma_f32_16x16x32_bf16 v[26:29], v[168:171], v[228:231], v[26:29]
	v_mfma_f32_16x16x32_bf16 v[14:17], v[150:153], v[236:239], v[14:17]
	v_mfma_f32_16x16x32_bf16 v[10:13], v[168:171], v[236:239], v[10:13]
	v_mfma_f32_16x16x32_bf16 v[54:57], v[172:175], v[188:191], v[54:57]
	v_mfma_f32_16x16x32_bf16 v[50:53], v[180:183], v[188:191], v[50:53]
	v_mfma_f32_16x16x32_bf16 v[38:41], v[172:175], v[216:219], v[38:41]
	v_mfma_f32_16x16x32_bf16 v[34:37], v[180:183], v[216:219], v[34:37]
	v_mfma_f32_16x16x32_bf16 v[22:25], v[172:175], v[224:227], v[22:25]
	v_mfma_f32_16x16x32_bf16 v[18:21], v[180:183], v[224:227], v[18:21]
	v_mfma_f32_16x16x32_bf16 v[6:9], v[172:175], v[232:235], v[6:9]
	v_mfma_f32_16x16x32_bf16 v[2:5], v[180:183], v[232:235], v[2:5]
	v_mfma_f32_16x16x32_bf16 v[54:57], v[176:179], v[212:215], v[54:57]
	v_mfma_f32_16x16x32_bf16 v[50:53], v[184:187], v[212:215], v[50:53]
	v_mfma_f32_16x16x32_bf16 v[38:41], v[176:179], v[220:223], v[38:41]
	v_mfma_f32_16x16x32_bf16 v[34:37], v[184:187], v[220:223], v[34:37]
	v_mfma_f32_16x16x32_bf16 v[22:25], v[176:179], v[228:231], v[22:25]
	v_mfma_f32_16x16x32_bf16 v[18:21], v[184:187], v[228:231], v[18:21]
	v_mfma_f32_16x16x32_bf16 v[6:9], v[176:179], v[236:239], v[6:9]
	v_mfma_f32_16x16x32_bf16 v[2:5], v[184:187], v[236:239], v[2:5]
	s_barrier
	s_add_i32 s54, s54, 2
	s_add_u32 s26, s26, 0x100
	s_addc_u32 s27, s27, 0
	s_add_u32 s52, s52, 0x100
	s_addc_u32 s53, s53, 0
	s_cmp_gt_u32 s54, 5
	s_cbranch_scc0 .LBB0_107
	s_and_b64 vcc, exec, s[16:17]
	s_cbranch_vccz .LBB0_110
	s_barrier

; #define PG8_STAGE(bufoff, gbase, voff) do { _Pragma("unroll") for (int _i = 0; _i < 2; ++_i) \
;         __builtin_amdgcn_global_load_lds((const unsigned*)((const char*)(gbase) + (voff)[_i]), (PG8_LAS unsigned*)(lds + (bufoff) + ldsw + _i * 8192), 16, 0, 0); } while (0)
; #define PG8_LDA(dst, b, h) do { _Pragma("unroll") for (int m = 0; m < 4; ++m) _Pragma("unroll") for (int k = 0; k < 2; ++k) dst[m][k] = *(const PG8_LAS bf16x8*)(lds + PG8_SA(b, h) + aoff + m * 2048 + k * 1024); } while (0)
; #define PG8_LDB(dst, b, h) do { _Pragma("unroll") for (int n = 0; n < 2; ++n) _Pragma("unroll") for (int k = 0; k < 2; ++k) dst[n][k] = *(const PG8_LAS bf16x8*)(lds + PG8_SB(b, h) + boff + n * 2048 + k * 1024); } while (0)
; #define PG8_MMA(ai, bj, At, Bt) do { __builtin_amdgcn_s_setprio(1); _Pragma("unroll") for (int m = 0; m < 4; ++m) _Pragma("unroll") for (int n = 0; n < 2; ++n) _Pragma("unroll") for (int k = 0; k < 2; ++k) \
;         acc[ai][bj][m][n] = __builtin_amdgcn_mfma_f32_16x16x32_bf16(Bt[n][k], At[m][k], acc[ai][bj][m][n], 0, 0, 0); __builtin_amdgcn_s_setprio(0); } while (0)
; #define PG8_BAR __builtin_amdgcn_s_barrier()
; template <class Epi, class Sched, bool ALIGN_EPI = false, bool SP2 = false>
; __device__ __forceinline__ void gemm_phase(PG8_LAS unsigned char* lds, const Gemm g, const Sched& S, const Epi& E, int wave_in) {
;     ...
;             PG8_LDB(B0, 0, 0); PG8_LDB(B1, 0, 1); PG8_SCHED; PG8_LDA(At, 0, 0); PG8_STAGE(PG8_SA(1, 1), a1 + hstepA, voffA);
;             PG8_WAIT_V(8); PG8_WAIT_L(0); PG8_BAR; PG8_MMA(0, 0, At, B0); PG8_MMA(0, 1, At, B1); PG8_BAR; PG8_SCHED;
;             PG8_LDA(At, 0, 1); PG8_STAGE(PG8_SB(0, 0), b2, voffB); PG8_STAGE(PG8_SB(0, 1), b2 + hstep, voffB); PG8_STAGE(PG8_SA(0, 0), a2, voffA);
;             PG8_WAIT_V(8); PG8_WAIT_L(0); PG8_BAR; PG8_MMA(1, 0, At, B0); PG8_MMA(1, 1, At, B1); PG8_BAR; PG8_SCHED;
;             PG8_LDB(B0, 1, 0); PG8_LDB(B1, 1, 1); PG8_SCHED; PG8_LDA(At, 1, 0); PG8_STAGE(PG8_SA(0, 1), a2 + hstepA, voffA);
;             PG8_WAIT_V(8); PG8_WAIT_L(0); PG8_BAR; PG8_MMA(0, 0, At, B0); PG8_MMA(0, 1, At, B1); PG8_BAR; PG8_SCHED;
;             PG8_LDA(At, 1, 1); PG8_STAGE(PG8_SB(1, 0), b3, voffB); PG8_STAGE(PG8_SB(1, 1), b3 + hstep, voffB); PG8_STAGE(PG8_SA(1, 0), a3, voffA);
;             PG8_WAIT_V(8); PG8_WAIT_L(0); PG8_BAR; PG8_MMA(1, 0, At, B0); PG8_MMA(1, 1, At, B1); PG8_BAR; PG8_SCHED;
.LBB0_128:
	s_add_u32 s24, s22, 0xfffe0080
	s_addc_u32 s25, s23, -1
	s_add_i32 s47, 0, 0x10000
	s_cmp_eq_u32 s46, 4
	s_cselect_b32 s27, s17, s25
	s_cselect_b32 s26, s42, s24
	s_cselect_b32 s25, s11, s45
	s_cselect_b32 s24, s43, s44
	s_add_i32 s50, 0, 0x14000
	v_add_u32_e32 v70, s47, v171
	v_add_u32_e32 v156, s50, v171
	ds_read_b128 v[58:61], v70
	ds_read_b128 v[62:65], v70 offset:1024
	ds_read_b128 v[66:69], v70 offset:2048
	ds_read_b128 v[70:73], v70 offset:3072
	ds_read_b128 v[174:177], v156
	ds_read_b128 v[178:181], v156 offset:1024
	ds_read_b128 v[182:185], v156 offset:2048
	ds_read_b128 v[186:189], v156 offset:3072
	v_lshl_add_u64 v[156:157], s[22:23], 0, v[152:153]
	s_add_i32 m0, s31, 0xc000
	ds_read_b128 v[190:193], v173
	ds_read_b128 v[212:215], v173 offset:1024
	ds_read_b128 v[216:219], v173 offset:2048
	ds_read_b128 v[220:223], v173 offset:3072
	ds_read_b128 v[224:227], v173 offset:4096
	ds_read_b128 v[228:231], v173 offset:5120
	ds_read_b128 v[232:235], v173 offset:6144
	ds_read_b128 v[236:239], v173 offset:7168
	global_load_lds_dwordx4 v[156:157], off
	v_lshl_add_u64 v[156:157], s[22:23], 0, v[154:155]
	s_add_i32 m0, s31, 0xe000
	s_nop 0
	global_load_lds_dwordx4 v[156:157], off
	s_waitcnt vmcnt(8)
	s_waitcnt lgkmcnt(0)
	s_barrier
	s_waitcnt lgkmcnt(0)
	v_mfma_f32_16x16x32_bf16 v[142:145], v[58:61], v[190:193], v[142:145]
	v_mfma_f32_16x16x32_bf16 v[138:141], v[66:69], v[190:193], v[138:141]
	v_mfma_f32_16x16x32_bf16 v[126:129], v[58:61], v[216:219], v[126:129]
	v_mfma_f32_16x16x32_bf16 v[122:125], v[66:69], v[216:219], v[122:125]
	v_mfma_f32_16x16x32_bf16 v[110:113], v[58:61], v[224:227], v[110:113]
	v_mfma_f32_16x16x32_bf16 v[106:109], v[66:69], v[224:227], v[106:109]
	v_mfma_f32_16x16x32_bf16 v[94:97], v[58:61], v[232:235], v[94:97]
	v_mfma_f32_16x16x32_bf16 v[90:93], v[66:69], v[232:235], v[90:93]
	v_mfma_f32_16x16x32_bf16 v[142:145], v[62:65], v[212:215], v[142:145]
	v_mfma_f32_16x16x32_bf16 v[138:141], v[70:73], v[212:215], v[138:141]
	v_mfma_f32_16x16x32_bf16 v[126:129], v[62:65], v[220:223], v[126:129]
	v_mfma_f32_16x16x32_bf16 v[122:125], v[70:73], v[220:223], v[122:125]
	v_mfma_f32_16x16x32_bf16 v[110:113], v[62:65], v[228:231], v[110:113]
	v_mfma_f32_16x16x32_bf16 v[106:109], v[70:73], v[228:231], v[106:109]
	v_mfma_f32_16x16x32_bf16 v[94:97], v[62:65], v[236:239], v[94:97]
	v_mfma_f32_16x16x32_bf16 v[90:93], v[70:73], v[236:239], v[90:93]
	v_mfma_f32_16x16x32_bf16 v[134:137], v[174:177], v[190:193], v[134:137]
	v_mfma_f32_16x16x32_bf16 v[130:133], v[182:185], v[190:193], v[130:133]
	v_mfma_f32_16x16x32_bf16 v[118:121], v[174:177], v[216:219], v[118:121]
	v_mfma_f32_16x16x32_bf16 v[114:117], v[182:185], v[216:219], v[114:117]
	v_mfma_f32_16x16x32_bf16 v[102:105], v[174:177], v[224:227], v[102:105]
	v_mfma_f32_16x16x32_bf16 v[98:101], v[182:185], v[224:227], v[98:101]
	v_mfma_f32_16x16x32_bf16 v[86:89], v[174:177], v[232:235], v[86:89]
	v_mfma_f32_16x16x32_bf16 v[82:85], v[182:185], v[232:235], v[82:85]
	v_mfma_f32_16x16x32_bf16 v[134:137], v[178:181], v[212:215], v[134:137]
	v_mfma_f32_16x16x32_bf16 v[130:133], v[186:189], v[212:215], v[130:133]
	v_mfma_f32_16x16x32_bf16 v[118:121], v[178:181], v[220:223], v[118:121]
	v_mfma_f32_16x16x32_bf16 v[114:117], v[186:189], v[220:223], v[114:117]
	v_mfma_f32_16x16x32_bf16 v[102:105], v[178:181], v[228:231], v[102:105]
	v_mfma_f32_16x16x32_bf16 v[98:101], v[186:189], v[228:231], v[98:101]
	v_mfma_f32_16x16x32_bf16 v[86:89], v[178:181], v[236:239], v[86:89]
	v_mfma_f32_16x16x32_bf16 v[82:85], v[186:189], v[236:239], v[82:85]
	s_barrier
	s_add_i32 s47, s47, s30
	v_lshl_add_u64 v[156:157], s[24:25], 0, v[0:1]
	s_mov_b32 m0, s47
	ds_read_b128 v[190:193], v173 offset:16384
	ds_read_b128 v[212:215], v173 offset:17408
	ds_read_b128 v[216:219], v173 offset:18432
	ds_read_b128 v[220:223], v173 offset:19456
	ds_read_b128 v[224:227], v173 offset:20480
	ds_read_b128 v[228:231], v173 offset:21504
	ds_read_b128 v[232:235], v173 offset:22528
	ds_read_b128 v[236:239], v173 offset:23552
	global_load_lds_dwordx4 v[156:157], off
	s_add_i32 m0, s47, 0x2000
	s_add_u32 s48, s24, 0x20000
	v_lshl_add_u64 v[168:169], s[24:25], 0, v[146:147]
	s_addc_u32 s49, s25, 0
	s_add_i32 s47, s50, s30
	global_load_lds_dwordx4 v[168:169], off
	v_lshl_add_u64 v[240:241], s[48:49], 0, v[0:1]
	s_mov_b32 m0, s47
	v_lshl_add_u64 v[242:243], s[26:27], 0, v[148:149]
	global_load_lds_dwordx4 v[240:241], off
	v_lshl_add_u64 v[240:241], s[48:49], 0, v[146:147]
	s_add_i32 m0, s47, 0x2000
	s_nop 0
	global_load_lds_dwordx4 v[240:241], off
	v_lshl_add_u64 v[240:241], s[26:27], 0, v[150:151]
	s_mov_b32 m0, s31
	s_nop 0
	global_load_lds_dwordx4 v[240:241], off
	s_mov_b32 m0, s34
	s_nop 0
	global_load_lds_dwordx4 v[242:243], off
	s_waitcnt vmcnt(8)
	s_waitcnt lgkmcnt(0)
	s_barrier
; #define PG8_STAGE(bufoff, gbase, voff) do { _Pragma("unroll") for (int _i = 0; _i < 2; ++_i) \
;         __builtin_amdgcn_global_load_lds((const unsigned*)((const char*)(gbase) + (voff)[_i]), (PG8_LAS unsigned*)(lds + (bufoff) + ldsw + _i * 8192), 16, 0, 0); } while (0)
; #define PG8_LDA(dst, b, h) do { _Pragma("unroll") for (int m = 0; m < 4; ++m) _Pragma("unroll") for (int k = 0; k < 2; ++k) dst[m][k] = *(const PG8_LAS bf16x8*)(lds + PG8_SA(b, h) + aoff + m * 2048 + k * 1024); } while (0)
; #define PG8_LDB(dst, b, h) do { _Pragma("unroll") for (int n = 0; n < 2; ++n) _Pragma("unroll") for (int k = 0; k < 2; ++k) dst[n][k] = *(const PG8_LAS bf16x8*)(lds + PG8_SB(b, h) + boff + n * 2048 + k * 1024); } while (0)
; #define PG8_MMA(ai, bj, At, Bt) do { __builtin_amdgcn_s_setprio(1); _Pragma("unroll") for (int m = 0; m < 4; ++m) _Pragma("unroll") for (int n = 0; n < 2; ++n) _Pragma("unroll") for (int k = 0; k < 2; ++k) \
;         acc[ai][bj][m][n] = __builtin_amdgcn_mfma_f32_16x16x32_bf16(Bt[n][k], At[m][k], acc[ai][bj][m][n], 0, 0, 0); __builtin_amdgcn_s_setprio(0); } while (0)
; #define PG8_BAR __builtin_amdgcn_s_barrier()
; template <class Epi, class Sched, bool ALIGN_EPI = false, bool SP2 = false>
; __device__ __forceinline__ void gemm_phase(PG8_LAS unsigned char* lds, const Gemm g, const Sched& S, const Epi& E, int wave_in) {
;     ...
;             PG8_LDB(B0, 0, 0); PG8_LDB(B1, 0, 1); PG8_SCHED; PG8_LDA(At, 0, 0); PG8_STAGE(PG8_SA(1, 1), a1 + hstepA, voffA);
;             PG8_WAIT_V(8); PG8_WAIT_L(0); PG8_BAR; PG8_MMA(0, 0, At, B0); PG8_MMA(0, 1, At, B1); PG8_BAR; PG8_SCHED;
;             PG8_LDA(At, 0, 1); PG8_STAGE(PG8_SB(0, 0), b2, voffB); PG8_STAGE(PG8_SB(0, 1), b2 + hstep, voffB); PG8_STAGE(PG8_SA(0, 0), a2, voffA);
;             PG8_WAIT_V(8); PG8_WAIT_L(0); PG8_BAR; PG8_MMA(1, 0, At, B0); PG8_MMA(1, 1, At, B1); PG8_BAR; PG8_SCHED;
;             PG8_LDB(B0, 1, 0); PG8_LDB(B1, 1, 1); PG8_SCHED; PG8_LDA(At, 1, 0); PG8_STAGE(PG8_SA(0, 1), a2 + hstepA, voffA);
;             PG8_WAIT_V(8); PG8_WAIT_L(0); PG8_BAR; PG8_MMA(0, 0, At, B0); PG8_MMA(0, 1, At, B1); PG8_BAR; PG8_SCHED;
;             PG8_LDA(At, 1, 1); PG8_STAGE(PG8_SB(1, 0), b3, voffB); PG8_STAGE(PG8_SB(1, 1), b3 + hstep, voffB); PG8_STAGE(PG8_SA(1, 0), a3, voffA);
;             PG8_WAIT_V(8); PG8_WAIT_L(0); PG8_BAR; PG8_MMA(1, 0, At, B0); PG8_MMA(1, 1, At, B1); PG8_BAR; PG8_SCHED;
	s_waitcnt lgkmcnt(0)
	v_mfma_f32_16x16x32_bf16 v[78:81], v[58:61], v[190:193], v[78:81]
	v_mfma_f32_16x16x32_bf16 v[74:77], v[66:69], v[190:193], v[74:77]
	v_mfma_f32_16x16x32_bf16 v[46:49], v[58:61], v[216:219], v[46:49]
	v_mfma_f32_16x16x32_bf16 v[42:45], v[66:69], v[216:219], v[42:45]
	v_mfma_f32_16x16x32_bf16 v[30:33], v[58:61], v[224:227], v[30:33]
	v_mfma_f32_16x16x32_bf16 v[26:29], v[66:69], v[224:227], v[26:29]
	v_mfma_f32_16x16x32_bf16 v[14:17], v[58:61], v[232:235], v[14:17]
	v_mfma_f32_16x16x32_bf16 v[10:13], v[66:69], v[232:235], v[10:13]
	v_mfma_f32_16x16x32_bf16 v[78:81], v[62:65], v[212:215], v[78:81]
	v_mfma_f32_16x16x32_bf16 v[74:77], v[70:73], v[212:215], v[74:77]
	v_mfma_f32_16x16x32_bf16 v[46:49], v[62:65], v[220:223], v[46:49]
	v_mfma_f32_16x16x32_bf16 v[42:45], v[70:73], v[220:223], v[42:45]
	v_mfma_f32_16x16x32_bf16 v[30:33], v[62:65], v[228:231], v[30:33]
	v_mfma_f32_16x16x32_bf16 v[26:29], v[70:73], v[228:231], v[26:29]
	v_mfma_f32_16x16x32_bf16 v[14:17], v[62:65], v[236:239], v[14:17]
	v_mfma_f32_16x16x32_bf16 v[10:13], v[70:73], v[236:239], v[10:13]
	v_mfma_f32_16x16x32_bf16 v[54:57], v[174:177], v[190:193], v[54:57]
	v_mfma_f32_16x16x32_bf16 v[50:53], v[182:185], v[190:193], v[50:53]
	v_mfma_f32_16x16x32_bf16 v[38:41], v[174:177], v[216:219], v[38:41]
	v_mfma_f32_16x16x32_bf16 v[34:37], v[182:185], v[216:219], v[34:37]
	v_mfma_f32_16x16x32_bf16 v[22:25], v[174:177], v[224:227], v[22:25]
	v_mfma_f32_16x16x32_bf16 v[18:21], v[182:185], v[224:227], v[18:21]
	v_mfma_f32_16x16x32_bf16 v[6:9], v[174:177], v[232:235], v[6:9]
	v_mfma_f32_16x16x32_bf16 v[2:5], v[182:185], v[232:235], v[2:5]
	v_mfma_f32_16x16x32_bf16 v[54:57], v[178:181], v[212:215], v[54:57]
	v_mfma_f32_16x16x32_bf16 v[50:53], v[186:189], v[212:215], v[50:53]
	v_mfma_f32_16x16x32_bf16 v[38:41], v[178:181], v[220:223], v[38:41]
	v_mfma_f32_16x16x32_bf16 v[34:37], v[186:189], v[220:223], v[34:37]
	v_mfma_f32_16x16x32_bf16 v[22:25], v[178:181], v[228:231], v[22:25]
	v_mfma_f32_16x16x32_bf16 v[18:21], v[186:189], v[228:231], v[18:21]
	v_mfma_f32_16x16x32_bf16 v[6:9], v[178:181], v[236:239], v[6:9]
	v_mfma_f32_16x16x32_bf16 v[2:5], v[186:189], v[236:239], v[2:5]
	s_barrier
	s_add_i32 s47, 0, 0x18000
	s_add_i32 s48, 0, 0x1c000
	v_add_u32_e32 v70, s47, v171
	v_add_u32_e32 v186, s48, v171
	ds_read_b128 v[58:61], v70
	ds_read_b128 v[62:65], v70 offset:1024
	ds_read_b128 v[66:69], v70 offset:2048
	ds_read_b128 v[70:73], v70 offset:3072
	ds_read_b128 v[174:177], v186
	ds_read_b128 v[178:181], v186 offset:1024
	ds_read_b128 v[182:185], v186 offset:2048
	ds_read_b128 v[186:189], v186 offset:3072
	s_add_u32 s26, s26, 0x20000
	s_addc_u32 s27, s27, 0
	s_mov_b32 m0, s35
	v_lshl_add_u64 v[244:245], s[26:27], 0, v[150:151]
	ds_read_b128 v[190:193], v173 offset:32768
	ds_read_b128 v[212:215], v173 offset:33792
	ds_read_b128 v[216:219], v173 offset:34816
	ds_read_b128 v[220:223], v173 offset:35840
	ds_read_b128 v[224:227], v173 offset:36864
	ds_read_b128 v[228:231], v173 offset:37888
	ds_read_b128 v[232:235], v173 offset:38912
	ds_read_b128 v[236:239], v173 offset:39936
	global_load_lds_dwordx4 v[244:245], off
	v_lshl_add_u64 v[244:245], s[26:27], 0, v[148:149]
	s_mov_b32 m0, s36
	s_nop 0
	global_load_lds_dwordx4 v[244:245], off
	s_waitcnt vmcnt(8)
	s_waitcnt lgkmcnt(0)
	s_barrier
	s_waitcnt lgkmcnt(0)
	v_mfma_f32_16x16x32_bf16 v[142:145], v[58:61], v[190:193], v[142:145]
	v_mfma_f32_16x16x32_bf16 v[138:141], v[66:69], v[190:193], v[138:141]
	v_mfma_f32_16x16x32_bf16 v[126:129], v[58:61], v[216:219], v[126:129]
	v_mfma_f32_16x16x32_bf16 v[122:125], v[66:69], v[216:219], v[122:125]
	v_mfma_f32_16x16x32_bf16 v[110:113], v[58:61], v[224:227], v[110:113]
	v_mfma_f32_16x16x32_bf16 v[106:109], v[66:69], v[224:227], v[106:109]
	v_mfma_f32_16x16x32_bf16 v[94:97], v[58:61], v[232:235], v[94:97]
	v_mfma_f32_16x16x32_bf16 v[90:93], v[66:69], v[232:235], v[90:93]
	v_mfma_f32_16x16x32_bf16 v[142:145], v[62:65], v[212:215], v[142:145]
	v_mfma_f32_16x16x32_bf16 v[138:141], v[70:73], v[212:215], v[138:141]
	v_mfma_f32_16x16x32_bf16 v[126:129], v[62:65], v[220:223], v[126:129]
	v_mfma_f32_16x16x32_bf16 v[122:125], v[70:73], v[220:223], v[122:125]
	v_mfma_f32_16x16x32_bf16 v[110:113], v[62:65], v[228:231], v[110:113]
	v_mfma_f32_16x16x32_bf16 v[106:109], v[70:73], v[228:231], v[106:109]
	v_mfma_f32_16x16x32_bf16 v[94:97], v[62:65], v[236:239], v[94:97]
	v_mfma_f32_16x16x32_bf16 v[90:93], v[70:73], v[236:239], v[90:93]
	v_mfma_f32_16x16x32_bf16 v[134:137], v[174:177], v[190:193], v[134:137]
	v_mfma_f32_16x16x32_bf16 v[130:133], v[182:185], v[190:193], v[130:133]
	v_mfma_f32_16x16x32_bf16 v[118:121], v[174:177], v[216:219], v[118:121]
	v_mfma_f32_16x16x32_bf16 v[114:117], v[182:185], v[216:219], v[114:117]
	v_mfma_f32_16x16x32_bf16 v[102:105], v[174:177], v[224:227], v[102:105]
	v_mfma_f32_16x16x32_bf16 v[98:101], v[182:185], v[224:227], v[98:101]
	v_mfma_f32_16x16x32_bf16 v[86:89], v[174:177], v[232:235], v[86:89]
	v_mfma_f32_16x16x32_bf16 v[82:85], v[182:185], v[232:235], v[82:85]
	v_mfma_f32_16x16x32_bf16 v[134:137], v[178:181], v[212:215], v[134:137]
	v_mfma_f32_16x16x32_bf16 v[130:133], v[186:189], v[212:215], v[130:133]
	v_mfma_f32_16x16x32_bf16 v[118:121], v[178:181], v[220:223], v[118:121]
	v_mfma_f32_16x16x32_bf16 v[114:117], v[186:189], v[220:223], v[114:117]
	v_mfma_f32_16x16x32_bf16 v[102:105], v[178:181], v[228:231], v[102:105]
	v_mfma_f32_16x16x32_bf16 v[98:101], v[186:189], v[228:231], v[98:101]
	v_mfma_f32_16x16x32_bf16 v[86:89], v[178:181], v[236:239], v[86:89]
	v_mfma_f32_16x16x32_bf16 v[82:85], v[186:189], v[236:239], v[82:85]
	s_barrier
; #define PG8_STAGE(bufoff, gbase, voff) do { _Pragma("unroll") for (int _i = 0; _i < 2; ++_i) \
;         __builtin_amdgcn_global_load_lds((const unsigned*)((const char*)(gbase) + (voff)[_i]), (PG8_LAS unsigned*)(lds + (bufoff) + ldsw + _i * 8192), 16, 0, 0); } while (0)
; #define PG8_LDA(dst, b, h) do { _Pragma("unroll") for (int m = 0; m < 4; ++m) _Pragma("unroll") for (int k = 0; k < 2; ++k) dst[m][k] = *(const PG8_LAS bf16x8*)(lds + PG8_SA(b, h) + aoff + m * 2048 + k * 1024); } while (0)
; #define PG8_LDB(dst, b, h) do { _Pragma("unroll") for (int n = 0; n < 2; ++n) _Pragma("unroll") for (int k = 0; k < 2; ++k) dst[n][k] = *(const PG8_LAS bf16x8*)(lds + PG8_SB(b, h) + boff + n * 2048 + k * 1024); } while (0)
; #define PG8_MMA(ai, bj, At, Bt) do { __builtin_amdgcn_s_setprio(1); _Pragma("unroll") for (int m = 0; m < 4; ++m) _Pragma("unroll") for (int n = 0; n < 2; ++n) _Pragma("unroll") for (int k = 0; k < 2; ++k) \
;         acc[ai][bj][m][n] = __builtin_amdgcn_mfma_f32_16x16x32_bf16(Bt[n][k], At[m][k], acc[ai][bj][m][n], 0, 0, 0); __builtin_amdgcn_s_setprio(0); } while (0)
; #define PG8_BAR __builtin_amdgcn_s_barrier()
; template <class Epi, class Sched, bool ALIGN_EPI = false, bool SP2 = false>
; __device__ __forceinline__ void gemm_phase(PG8_LAS unsigned char* lds, const Gemm g, const Sched& S, const Epi& E, int wave_in) {
;     ...
;             PG8_LDB(B0, 0, 0); PG8_LDB(B1, 0, 1); PG8_SCHED; PG8_LDA(At, 0, 0); PG8_STAGE(PG8_SA(1, 1), a1 + hstepA, voffA);
;             PG8_WAIT_V(8); PG8_WAIT_L(0); PG8_BAR; PG8_MMA(0, 0, At, B0); PG8_MMA(0, 1, At, B1); PG8_BAR; PG8_SCHED;
;             PG8_LDA(At, 0, 1); PG8_STAGE(PG8_SB(0, 0), b2, voffB); PG8_STAGE(PG8_SB(0, 1), b2 + hstep, voffB); PG8_STAGE(PG8_SA(0, 0), a2, voffA);
;             PG8_WAIT_V(8); PG8_WAIT_L(0); PG8_BAR; PG8_MMA(1, 0, At, B0); PG8_MMA(1, 1, At, B1); PG8_BAR; PG8_SCHED;
;             PG8_LDB(B0, 1, 0); PG8_LDB(B1, 1, 1); PG8_SCHED; PG8_LDA(At, 1, 0); PG8_STAGE(PG8_SA(0, 1), a2 + hstepA, voffA);
;             PG8_WAIT_V(8); PG8_WAIT_L(0); PG8_BAR; PG8_MMA(0, 0, At, B0); PG8_MMA(0, 1, At, B1); PG8_BAR; PG8_SCHED;
;             PG8_LDA(At, 1, 1); PG8_STAGE(PG8_SB(1, 0), b3, voffB); PG8_STAGE(PG8_SB(1, 1), b3 + hstep, voffB); PG8_STAGE(PG8_SA(1, 0), a3, voffA);
;             PG8_WAIT_V(8); PG8_WAIT_L(0); PG8_BAR; PG8_MMA(1, 0, At, B0); PG8_MMA(1, 1, At, B1); PG8_BAR; PG8_SCHED;
	s_add_i32 s26, s47, s30
	v_lshl_add_u64 v[156:157], v[156:157], 0, s[84:85]
	s_mov_b32 m0, s26
	ds_read_b128 v[190:193], v173 offset:49152
	ds_read_b128 v[212:215], v173 offset:50176
	ds_read_b128 v[216:219], v173 offset:51200
	ds_read_b128 v[220:223], v173 offset:52224
	ds_read_b128 v[224:227], v173 offset:53248
	ds_read_b128 v[228:231], v173 offset:54272
	ds_read_b128 v[232:235], v173 offset:55296
	ds_read_b128 v[236:239], v173 offset:56320
	global_load_lds_dwordx4 v[156:157], off
	s_add_i32 m0, s26, 0x2000
	s_add_u32 s24, s24, 0x20080
	v_lshl_add_u64 v[156:157], v[168:169], 0, s[84:85]
	s_addc_u32 s25, s25, 0
	s_add_i32 s26, s48, s30
	global_load_lds_dwordx4 v[156:157], off
	v_lshl_add_u64 v[156:157], s[24:25], 0, v[0:1]
	s_mov_b32 m0, s26
	s_nop 0
	global_load_lds_dwordx4 v[156:157], off
	v_lshl_add_u64 v[156:157], s[24:25], 0, v[146:147]
	s_add_i32 m0, s26, 0x2000
	s_nop 0
	global_load_lds_dwordx4 v[156:157], off
	v_lshl_add_u64 v[156:157], v[240:241], 0, s[84:85]
	s_mov_b32 m0, s37
	s_nop 0
	global_load_lds_dwordx4 v[156:157], off
	v_lshl_add_u64 v[156:157], v[242:243], 0, s[84:85]
	s_mov_b32 m0, s38
	s_nop 0
	global_load_lds_dwordx4 v[156:157], off
	s_waitcnt vmcnt(8)
	s_waitcnt lgkmcnt(0)
	s_barrier
	s_waitcnt lgkmcnt(0)
	v_mfma_f32_16x16x32_bf16 v[78:81], v[58:61], v[190:193], v[78:81]
	v_mfma_f32_16x16x32_bf16 v[74:77], v[66:69], v[190:193], v[74:77]
	v_mfma_f32_16x16x32_bf16 v[46:49], v[58:61], v[216:219], v[46:49]
	v_mfma_f32_16x16x32_bf16 v[42:45], v[66:69], v[216:219], v[42:45]
	v_mfma_f32_16x16x32_bf16 v[30:33], v[58:61], v[224:227], v[30:33]
	v_mfma_f32_16x16x32_bf16 v[26:29], v[66:69], v[224:227], v[26:29]
	v_mfma_f32_16x16x32_bf16 v[14:17], v[58:61], v[232:235], v[14:17]
	v_mfma_f32_16x16x32_bf16 v[10:13], v[66:69], v[232:235], v[10:13]
	v_mfma_f32_16x16x32_bf16 v[78:81], v[62:65], v[212:215], v[78:81]
	v_mfma_f32_16x16x32_bf16 v[74:77], v[70:73], v[212:215], v[74:77]
	v_mfma_f32_16x16x32_bf16 v[46:49], v[62:65], v[220:223], v[46:49]
	v_mfma_f32_16x16x32_bf16 v[42:45], v[70:73], v[220:223], v[42:45]
	v_mfma_f32_16x16x32_bf16 v[30:33], v[62:65], v[228:231], v[30:33]
	v_mfma_f32_16x16x32_bf16 v[26:29], v[70:73], v[228:231], v[26:29]
	v_mfma_f32_16x16x32_bf16 v[14:17], v[62:65], v[236:239], v[14:17]
	v_mfma_f32_16x16x32_bf16 v[10:13], v[70:73], v[236:239], v[10:13]
	v_mfma_f32_16x16x32_bf16 v[54:57], v[174:177], v[190:193], v[54:57]
	v_mfma_f32_16x16x32_bf16 v[50:53], v[182:185], v[190:193], v[50:53]
	v_mfma_f32_16x16x32_bf16 v[38:41], v[174:177], v[216:219], v[38:41]
	v_mfma_f32_16x16x32_bf16 v[34:37], v[182:185], v[216:219], v[34:37]
	v_mfma_f32_16x16x32_bf16 v[22:25], v[174:177], v[224:227], v[22:25]
	v_mfma_f32_16x16x32_bf16 v[18:21], v[182:185], v[224:227], v[18:21]
	v_mfma_f32_16x16x32_bf16 v[6:9], v[174:177], v[232:235], v[6:9]
	v_mfma_f32_16x16x32_bf16 v[2:5], v[182:185], v[232:235], v[2:5]
	v_mfma_f32_16x16x32_bf16 v[54:57], v[178:181], v[212:215], v[54:57]
	v_mfma_f32_16x16x32_bf16 v[50:53], v[186:189], v[212:215], v[50:53]
	v_mfma_f32_16x16x32_bf16 v[38:41], v[178:181], v[220:223], v[38:41]
	v_mfma_f32_16x16x32_bf16 v[34:37], v[186:189], v[220:223], v[34:37]
	v_mfma_f32_16x16x32_bf16 v[22:25], v[178:181], v[228:231], v[22:25]
	v_mfma_f32_16x16x32_bf16 v[18:21], v[186:189], v[228:231], v[18:21]
	v_mfma_f32_16x16x32_bf16 v[6:9], v[178:181], v[236:239], v[6:9]
	v_mfma_f32_16x16x32_bf16 v[2:5], v[186:189], v[236:239], v[2:5]
	s_barrier
	s_add_i32 s46, s46, 2
	s_add_u32 s22, s22, 0x100
	s_addc_u32 s23, s23, 0
	s_add_u32 s44, s44, 0x100
	s_addc_u32 s45, s45, 0
	s_cmp_gt_u32 s46, 5
	s_cbranch_scc0 .LBB0_128
	s_and_b64 vcc, exec, s[8:9]
	v_readlane_b32 s26, v254, 6
	v_readlane_b32 s27, v254, 7
	s_cbranch_vccz .LBB0_131
	s_barrier

; #define PG8_STAGE(bufoff, gbase, voff) do { _Pragma("unroll") for (int _i = 0; _i < 2; ++_i) \
;         __builtin_amdgcn_global_load_lds((const unsigned*)((const char*)(gbase) + (voff)[_i]), (PG8_LAS unsigned*)(lds + (bufoff) + ldsw + _i * 8192), 16, 0, 0); } while (0)
; #define PG8_LDA(dst, b, h) do { _Pragma("unroll") for (int m = 0; m < 4; ++m) _Pragma("unroll") for (int k = 0; k < 2; ++k) dst[m][k] = *(const PG8_LAS bf16x8*)(lds + PG8_SA(b, h) + aoff + m * 2048 + k * 1024); } while (0)
; #define PG8_LDB(dst, b, h) do { _Pragma("unroll") for (int n = 0; n < 2; ++n) _Pragma("unroll") for (int k = 0; k < 2; ++k) dst[n][k] = *(const PG8_LAS bf16x8*)(lds + PG8_SB(b, h) + boff + n * 2048 + k * 1024); } while (0)
; #define PG8_MMA(ai, bj, At, Bt) do { __builtin_amdgcn_s_setprio(1); _Pragma("unroll") for (int m = 0; m < 4; ++m) _Pragma("unroll") for (int n = 0; n < 2; ++n) _Pragma("unroll") for (int k = 0; k < 2; ++k) \
;         acc[ai][bj][m][n] = __builtin_amdgcn_mfma_f32_16x16x32_bf16(Bt[n][k], At[m][k], acc[ai][bj][m][n], 0, 0, 0); __builtin_amdgcn_s_setprio(0); } while (0)
; #define PG8_BAR __builtin_amdgcn_s_barrier()
; template <class Epi, class Sched, bool ALIGN_EPI = false, bool SP2 = false>
; __device__ __forceinline__ void gemm_phase(PG8_LAS unsigned char* lds, const Gemm g, const Sched& S, const Epi& E, int wave_in) {
;     ...
;             PG8_LDB(B0, 0, 0); PG8_LDB(B1, 0, 1); PG8_SCHED; PG8_LDA(At, 0, 0); PG8_STAGE(PG8_SA(1, 1), a1 + hstepA, voffA);
;             PG8_WAIT_V(8); PG8_WAIT_L(0); PG8_BAR; PG8_MMA(0, 0, At, B0); PG8_MMA(0, 1, At, B1); PG8_BAR; PG8_SCHED;
;             PG8_LDA(At, 0, 1); PG8_STAGE(PG8_SB(0, 0), b2, voffB); PG8_STAGE(PG8_SB(0, 1), b2 + hstep, voffB); PG8_STAGE(PG8_SA(0, 0), a2, voffA);
;             PG8_WAIT_V(8); PG8_WAIT_L(0); PG8_BAR; PG8_MMA(1, 0, At, B0); PG8_MMA(1, 1, At, B1); PG8_BAR; PG8_SCHED;
;             PG8_LDB(B0, 1, 0); PG8_LDB(B1, 1, 1); PG8_SCHED; PG8_LDA(At, 1, 0); PG8_STAGE(PG8_SA(0, 1), a2 + hstepA, voffA);
;             PG8_WAIT_V(8); PG8_WAIT_L(0); PG8_BAR; PG8_MMA(0, 0, At, B0); PG8_MMA(0, 1, At, B1); PG8_BAR; PG8_SCHED;
;             PG8_LDA(At, 1, 1); PG8_STAGE(PG8_SB(1, 0), b3, voffB); PG8_STAGE(PG8_SB(1, 1), b3 + hstep, voffB); PG8_STAGE(PG8_SA(1, 0), a3, voffA);
;             PG8_WAIT_V(8); PG8_WAIT_L(0); PG8_BAR; PG8_MMA(1, 0, At, B0); PG8_MMA(1, 1, At, B1); PG8_BAR; PG8_SCHED;
.LBB0_277:
	s_add_u32 s2, s0, 0xfff80080
	s_addc_u32 s3, s1, -1
	s_add_i32 s41, 0, 0x10000
	s_cmp_eq_u32 s40, 28
	s_cselect_b32 s5, s19, s3
	s_cselect_b32 s4, s36, s2
	s_cselect_b32 s3, s17, s39
	s_cselect_b32 s2, s37, s38
	s_add_i32 s44, 0, 0x14000
	v_add_u32_e32 v46, s41, v181
	v_add_u32_e32 v156, s44, v181
	ds_read_b128 v[26:29], v46
	ds_read_b128 v[30:33], v46 offset:1024
	ds_read_b128 v[42:45], v46 offset:2048
	ds_read_b128 v[46:49], v46 offset:3072
	ds_read_b128 v[168:171], v156
	ds_read_b128 v[172:175], v156 offset:1024
	ds_read_b128 v[176:179], v156 offset:2048
	ds_read_b128 v[184:187], v156 offset:3072
	v_lshl_add_u64 v[156:157], s[0:1], 0, v[152:153]
	s_add_i32 m0, s25, 0xc000
	ds_read_b128 v[188:191], v183
	ds_read_b128 v[212:215], v183 offset:1024
	ds_read_b128 v[216:219], v183 offset:2048
	ds_read_b128 v[220:223], v183 offset:3072
	ds_read_b128 v[224:227], v183 offset:4096
	ds_read_b128 v[228:231], v183 offset:5120
	ds_read_b128 v[232:235], v183 offset:6144
	ds_read_b128 v[236:239], v183 offset:7168
	global_load_lds_dwordx4 v[156:157], off
	v_lshl_add_u64 v[156:157], s[0:1], 0, v[154:155]
	s_add_i32 m0, s25, 0xe000
	s_nop 0
	global_load_lds_dwordx4 v[156:157], off
	s_waitcnt vmcnt(8)
	s_waitcnt lgkmcnt(0)
	s_barrier
	s_waitcnt lgkmcnt(0)
	v_mfma_f32_16x16x32_bf16 v[142:145], v[26:29], v[188:191], v[142:145]
	v_mfma_f32_16x16x32_bf16 v[138:141], v[42:45], v[188:191], v[138:141]
	v_mfma_f32_16x16x32_bf16 v[126:129], v[26:29], v[216:219], v[126:129]
	v_mfma_f32_16x16x32_bf16 v[122:125], v[42:45], v[216:219], v[122:125]
	v_mfma_f32_16x16x32_bf16 v[110:113], v[26:29], v[224:227], v[110:113]
	v_mfma_f32_16x16x32_bf16 v[106:109], v[42:45], v[224:227], v[106:109]
	v_mfma_f32_16x16x32_bf16 v[94:97], v[26:29], v[232:235], v[94:97]
	v_mfma_f32_16x16x32_bf16 v[90:93], v[42:45], v[232:235], v[90:93]
	v_mfma_f32_16x16x32_bf16 v[142:145], v[30:33], v[212:215], v[142:145]
	v_mfma_f32_16x16x32_bf16 v[138:141], v[46:49], v[212:215], v[138:141]
	v_mfma_f32_16x16x32_bf16 v[126:129], v[30:33], v[220:223], v[126:129]
	v_mfma_f32_16x16x32_bf16 v[122:125], v[46:49], v[220:223], v[122:125]
	v_mfma_f32_16x16x32_bf16 v[110:113], v[30:33], v[228:231], v[110:113]
	v_mfma_f32_16x16x32_bf16 v[106:109], v[46:49], v[228:231], v[106:109]
	v_mfma_f32_16x16x32_bf16 v[94:97], v[30:33], v[236:239], v[94:97]
	v_mfma_f32_16x16x32_bf16 v[90:93], v[46:49], v[236:239], v[90:93]
	v_mfma_f32_16x16x32_bf16 v[134:137], v[168:171], v[188:191], v[134:137]
	v_mfma_f32_16x16x32_bf16 v[130:133], v[176:179], v[188:191], v[130:133]
	v_mfma_f32_16x16x32_bf16 v[118:121], v[168:171], v[216:219], v[118:121]
	v_mfma_f32_16x16x32_bf16 v[114:117], v[176:179], v[216:219], v[114:117]
	v_mfma_f32_16x16x32_bf16 v[102:105], v[168:171], v[224:227], v[102:105]
	v_mfma_f32_16x16x32_bf16 v[98:101], v[176:179], v[224:227], v[98:101]
	v_mfma_f32_16x16x32_bf16 v[86:89], v[168:171], v[232:235], v[86:89]
	v_mfma_f32_16x16x32_bf16 v[82:85], v[176:179], v[232:235], v[82:85]
	v_mfma_f32_16x16x32_bf16 v[134:137], v[172:175], v[212:215], v[134:137]
	v_mfma_f32_16x16x32_bf16 v[130:133], v[184:187], v[212:215], v[130:133]
	v_mfma_f32_16x16x32_bf16 v[118:121], v[172:175], v[220:223], v[118:121]
	v_mfma_f32_16x16x32_bf16 v[114:117], v[184:187], v[220:223], v[114:117]
	v_mfma_f32_16x16x32_bf16 v[102:105], v[172:175], v[228:231], v[102:105]
	v_mfma_f32_16x16x32_bf16 v[98:101], v[184:187], v[228:231], v[98:101]
	v_mfma_f32_16x16x32_bf16 v[86:89], v[172:175], v[236:239], v[86:89]
	v_mfma_f32_16x16x32_bf16 v[82:85], v[184:187], v[236:239], v[82:85]
	s_barrier
	s_add_i32 s41, s41, s24
	v_lshl_add_u64 v[156:157], s[2:3], 0, v[0:1]
	s_mov_b32 m0, s41
	ds_read_b128 v[188:191], v183 offset:16384
	ds_read_b128 v[212:215], v183 offset:17408
	ds_read_b128 v[216:219], v183 offset:18432
	ds_read_b128 v[220:223], v183 offset:19456
	ds_read_b128 v[224:227], v183 offset:20480
	ds_read_b128 v[228:231], v183 offset:21504
	ds_read_b128 v[232:235], v183 offset:22528
	ds_read_b128 v[236:239], v183 offset:23552
	global_load_lds_dwordx4 v[156:157], off
	s_add_i32 m0, s41, 0x2000
	s_add_u32 s42, s2, 0x80000
	v_lshl_add_u64 v[192:193], s[2:3], 0, v[146:147]
	s_addc_u32 s43, s3, 0
	s_add_i32 s41, s44, s24
	global_load_lds_dwordx4 v[192:193], off
	v_lshl_add_u64 v[240:241], s[42:43], 0, v[0:1]
	s_mov_b32 m0, s41
	v_lshl_add_u64 v[242:243], s[4:5], 0, v[148:149]
	global_load_lds_dwordx4 v[240:241], off
	v_lshl_add_u64 v[240:241], s[42:43], 0, v[146:147]
	s_add_i32 m0, s41, 0x2000
	s_nop 0
	global_load_lds_dwordx4 v[240:241], off
	v_lshl_add_u64 v[240:241], s[4:5], 0, v[150:151]
	s_mov_b32 m0, s25
	s_nop 0
	global_load_lds_dwordx4 v[240:241], off
	s_mov_b32 m0, s26
	s_nop 0
	global_load_lds_dwordx4 v[242:243], off
	s_waitcnt vmcnt(8)
	s_waitcnt lgkmcnt(0)
	s_barrier
; #define PG8_STAGE(bufoff, gbase, voff) do { _Pragma("unroll") for (int _i = 0; _i < 2; ++_i) \
;         __builtin_amdgcn_global_load_lds((const unsigned*)((const char*)(gbase) + (voff)[_i]), (PG8_LAS unsigned*)(lds + (bufoff) + ldsw + _i * 8192), 16, 0, 0); } while (0)
; #define PG8_LDA(dst, b, h) do { _Pragma("unroll") for (int m = 0; m < 4; ++m) _Pragma("unroll") for (int k = 0; k < 2; ++k) dst[m][k] = *(const PG8_LAS bf16x8*)(lds + PG8_SA(b, h) + aoff + m * 2048 + k * 1024); } while (0)
; #define PG8_LDB(dst, b, h) do { _Pragma("unroll") for (int n = 0; n < 2; ++n) _Pragma("unroll") for (int k = 0; k < 2; ++k) dst[n][k] = *(const PG8_LAS bf16x8*)(lds + PG8_SB(b, h) + boff + n * 2048 + k * 1024); } while (0)
; #define PG8_MMA(ai, bj, At, Bt) do { __builtin_amdgcn_s_setprio(1); _Pragma("unroll") for (int m = 0; m < 4; ++m) _Pragma("unroll") for (int n = 0; n < 2; ++n) _Pragma("unroll") for (int k = 0; k < 2; ++k) \
;         acc[ai][bj][m][n] = __builtin_amdgcn_mfma_f32_16x16x32_bf16(Bt[n][k], At[m][k], acc[ai][bj][m][n], 0, 0, 0); __builtin_amdgcn_s_setprio(0); } while (0)
; #define PG8_WAIT_V(n) asm volatile("s_waitcnt vmcnt(" #n ")" ::: "memory")
; #define PG8_WAIT_L(n) asm volatile("s_waitcnt lgkmcnt(" #n ")" ::: "memory")
; #define PG8_BAR __builtin_amdgcn_s_barrier()
; #define PG8_SCHED __builtin_amdgcn_sched_barrier(0)
; template <class Epi, class Sched, bool ALIGN_EPI = false, bool SP2 = false>
; __device__ __forceinline__ void gemm_phase(PG8_LAS unsigned char* lds, const Gemm g, const Sched& S, const Epi& E, int wave_in) {
;     ...
;             PG8_WAIT_V(8); PG8_WAIT_L(0); PG8_BAR; PG8_MMA(1, 0, At, B0); PG8_MMA(1, 1, At, B1); PG8_BAR; PG8_SCHED;
;             PG8_LDB(B0, 1, 0); PG8_LDB(B1, 1, 1); PG8_SCHED; PG8_LDA(At, 1, 0); PG8_STAGE(PG8_SA(0, 1), a2 + hstepA, voffA);
;             PG8_WAIT_V(8); PG8_WAIT_L(0); PG8_BAR; PG8_MMA(0, 0, At, B0); PG8_MMA(0, 1, At, B1); PG8_BAR; PG8_SCHED;
	s_waitcnt lgkmcnt(0)
	v_mfma_f32_16x16x32_bf16 v[78:81], v[26:29], v[188:191], v[78:81]
	v_mfma_f32_16x16x32_bf16 v[74:77], v[42:45], v[188:191], v[74:77]
	v_mfma_f32_16x16x32_bf16 v[62:65], v[26:29], v[216:219], v[62:65]
	v_mfma_f32_16x16x32_bf16 v[58:61], v[42:45], v[216:219], v[58:61]
	v_mfma_f32_16x16x32_bf16 v[38:41], v[26:29], v[224:227], v[38:41]
	v_mfma_f32_16x16x32_bf16 v[34:37], v[42:45], v[224:227], v[34:37]
	v_mfma_f32_16x16x32_bf16 v[14:17], v[26:29], v[232:235], v[14:17]
	v_mfma_f32_16x16x32_bf16 v[10:13], v[42:45], v[232:235], v[10:13]
	v_mfma_f32_16x16x32_bf16 v[78:81], v[30:33], v[212:215], v[78:81]
	v_mfma_f32_16x16x32_bf16 v[74:77], v[46:49], v[212:215], v[74:77]
	v_mfma_f32_16x16x32_bf16 v[62:65], v[30:33], v[220:223], v[62:65]
	v_mfma_f32_16x16x32_bf16 v[58:61], v[46:49], v[220:223], v[58:61]
	v_mfma_f32_16x16x32_bf16 v[38:41], v[30:33], v[228:231], v[38:41]
	v_mfma_f32_16x16x32_bf16 v[34:37], v[46:49], v[228:231], v[34:37]
	v_mfma_f32_16x16x32_bf16 v[14:17], v[30:33], v[236:239], v[14:17]
	v_mfma_f32_16x16x32_bf16 v[10:13], v[46:49], v[236:239], v[10:13]
	v_mfma_f32_16x16x32_bf16 v[22:25], v[168:171], v[224:227], v[22:25]
	v_mfma_f32_16x16x32_bf16 v[18:21], v[176:179], v[224:227], v[18:21]
	v_mfma_f32_16x16x32_bf16 v[6:9], v[168:171], v[232:235], v[6:9]
	v_mfma_f32_16x16x32_bf16 v[2:5], v[176:179], v[232:235], v[2:5]
	v_mfma_f32_16x16x32_bf16 v[26:29], v[168:171], v[188:191], v[70:73]
	v_mfma_f32_16x16x32_bf16 v[30:33], v[176:179], v[188:191], v[66:69]
	v_mfma_f32_16x16x32_bf16 v[42:45], v[168:171], v[216:219], v[54:57]
	v_mfma_f32_16x16x32_bf16 v[46:49], v[176:179], v[216:219], v[50:53]
	v_mfma_f32_16x16x32_bf16 v[22:25], v[172:175], v[228:231], v[22:25]
	v_mfma_f32_16x16x32_bf16 v[18:21], v[184:187], v[228:231], v[18:21]
	v_mfma_f32_16x16x32_bf16 v[6:9], v[172:175], v[236:239], v[6:9]
	v_mfma_f32_16x16x32_bf16 v[2:5], v[184:187], v[236:239], v[2:5]
	v_mfma_f32_16x16x32_bf16 v[26:29], v[172:175], v[212:215], v[26:29]
	v_mfma_f32_16x16x32_bf16 v[30:33], v[184:187], v[212:215], v[30:33]
	v_mfma_f32_16x16x32_bf16 v[42:45], v[172:175], v[220:223], v[42:45]
	v_mfma_f32_16x16x32_bf16 v[46:49], v[184:187], v[220:223], v[46:49]
	s_barrier
	s_add_i32 s41, 0, 0x18000
	s_add_i32 s42, 0, 0x1c000
	v_add_u32_e32 v70, s41, v181
	v_add_u32_e32 v184, s42, v181
	ds_read_b128 v[50:53], v70
	ds_read_b128 v[54:57], v70 offset:1024
	ds_read_b128 v[66:69], v70 offset:2048
	ds_read_b128 v[70:73], v70 offset:3072
	ds_read_b128 v[168:171], v184
	ds_read_b128 v[172:175], v184 offset:1024
	ds_read_b128 v[176:179], v184 offset:2048
	ds_read_b128 v[184:187], v184 offset:3072
	s_add_u32 s4, s4, 0x80000
	s_addc_u32 s5, s5, 0
	s_mov_b32 m0, s27
	v_lshl_add_u64 v[244:245], s[4:5], 0, v[150:151]
	ds_read_b128 v[188:191], v183 offset:32768
	ds_read_b128 v[212:215], v183 offset:33792
	ds_read_b128 v[216:219], v183 offset:34816
	ds_read_b128 v[220:223], v183 offset:35840
	ds_read_b128 v[224:227], v183 offset:36864
	ds_read_b128 v[228:231], v183 offset:37888
	ds_read_b128 v[232:235], v183 offset:38912
	ds_read_b128 v[236:239], v183 offset:39936
	global_load_lds_dwordx4 v[244:245], off
	v_lshl_add_u64 v[244:245], s[4:5], 0, v[148:149]
	s_mov_b32 m0, s28
	s_nop 0
	global_load_lds_dwordx4 v[244:245], off
	s_waitcnt vmcnt(8)
	s_waitcnt lgkmcnt(0)
	s_barrier
	s_waitcnt lgkmcnt(0)
	v_mfma_f32_16x16x32_bf16 v[142:145], v[50:53], v[188:191], v[142:145]
	v_mfma_f32_16x16x32_bf16 v[138:141], v[66:69], v[188:191], v[138:141]
	v_mfma_f32_16x16x32_bf16 v[126:129], v[50:53], v[216:219], v[126:129]
	v_mfma_f32_16x16x32_bf16 v[122:125], v[66:69], v[216:219], v[122:125]
	v_mfma_f32_16x16x32_bf16 v[110:113], v[50:53], v[224:227], v[110:113]
	v_mfma_f32_16x16x32_bf16 v[106:109], v[66:69], v[224:227], v[106:109]
	v_mfma_f32_16x16x32_bf16 v[94:97], v[50:53], v[232:235], v[94:97]
	v_mfma_f32_16x16x32_bf16 v[90:93], v[66:69], v[232:235], v[90:93]
	v_mfma_f32_16x16x32_bf16 v[142:145], v[54:57], v[212:215], v[142:145]
	v_mfma_f32_16x16x32_bf16 v[138:141], v[70:73], v[212:215], v[138:141]
	v_mfma_f32_16x16x32_bf16 v[126:129], v[54:57], v[220:223], v[126:129]
	v_mfma_f32_16x16x32_bf16 v[122:125], v[70:73], v[220:223], v[122:125]
	v_mfma_f32_16x16x32_bf16 v[110:113], v[54:57], v[228:231], v[110:113]
	v_mfma_f32_16x16x32_bf16 v[106:109], v[70:73], v[228:231], v[106:109]
	v_mfma_f32_16x16x32_bf16 v[94:97], v[54:57], v[236:239], v[94:97]
	v_mfma_f32_16x16x32_bf16 v[90:93], v[70:73], v[236:239], v[90:93]
	v_mfma_f32_16x16x32_bf16 v[134:137], v[168:171], v[188:191], v[134:137]
	v_mfma_f32_16x16x32_bf16 v[130:133], v[176:179], v[188:191], v[130:133]
	v_mfma_f32_16x16x32_bf16 v[118:121], v[168:171], v[216:219], v[118:121]
	v_mfma_f32_16x16x32_bf16 v[114:117], v[176:179], v[216:219], v[114:117]
	v_mfma_f32_16x16x32_bf16 v[102:105], v[168:171], v[224:227], v[102:105]
	v_mfma_f32_16x16x32_bf16 v[98:101], v[176:179], v[224:227], v[98:101]
	v_mfma_f32_16x16x32_bf16 v[86:89], v[168:171], v[232:235], v[86:89]
	v_mfma_f32_16x16x32_bf16 v[82:85], v[176:179], v[232:235], v[82:85]
	v_mfma_f32_16x16x32_bf16 v[134:137], v[172:175], v[212:215], v[134:137]
	v_mfma_f32_16x16x32_bf16 v[130:133], v[184:187], v[212:215], v[130:133]
	v_mfma_f32_16x16x32_bf16 v[118:121], v[172:175], v[220:223], v[118:121]
	v_mfma_f32_16x16x32_bf16 v[114:117], v[184:187], v[220:223], v[114:117]
	v_mfma_f32_16x16x32_bf16 v[102:105], v[172:175], v[228:231], v[102:105]
	v_mfma_f32_16x16x32_bf16 v[98:101], v[184:187], v[228:231], v[98:101]
	v_mfma_f32_16x16x32_bf16 v[86:89], v[172:175], v[236:239], v[86:89]
	v_mfma_f32_16x16x32_bf16 v[82:85], v[184:187], v[236:239], v[82:85]
	s_barrier
; #define PG8_STAGE(bufoff, gbase, voff) do { _Pragma("unroll") for (int _i = 0; _i < 2; ++_i) \
;         __builtin_amdgcn_global_load_lds((const unsigned*)((const char*)(gbase) + (voff)[_i]), (PG8_LAS unsigned*)(lds + (bufoff) + ldsw + _i * 8192), 16, 0, 0); } while (0)
; #define PG8_LDA(dst, b, h) do { _Pragma("unroll") for (int m = 0; m < 4; ++m) _Pragma("unroll") for (int k = 0; k < 2; ++k) dst[m][k] = *(const PG8_LAS bf16x8*)(lds + PG8_SA(b, h) + aoff + m * 2048 + k * 1024); } while (0)
; #define PG8_MMA(ai, bj, At, Bt) do { __builtin_amdgcn_s_setprio(1); _Pragma("unroll") for (int m = 0; m < 4; ++m) _Pragma("unroll") for (int n = 0; n < 2; ++n) _Pragma("unroll") for (int k = 0; k < 2; ++k) \
;         acc[ai][bj][m][n] = __builtin_amdgcn_mfma_f32_16x16x32_bf16(Bt[n][k], At[m][k], acc[ai][bj][m][n], 0, 0, 0); __builtin_amdgcn_s_setprio(0); } while (0)
; #define PG8_WAIT_V(n) asm volatile("s_waitcnt vmcnt(" #n ")" ::: "memory")
; #define PG8_WAIT_L(n) asm volatile("s_waitcnt lgkmcnt(" #n ")" ::: "memory")
; #define PG8_BAR __builtin_amdgcn_s_barrier()
; #define PG8_SCHED __builtin_amdgcn_sched_barrier(0)
; template <class Epi, class Sched, bool ALIGN_EPI = false, bool SP2 = false>
; __device__ __forceinline__ void gemm_phase(PG8_LAS unsigned char* lds, const Gemm g, const Sched& S, const Epi& E, int wave_in) {
;     ...
;         for (int t = 0; t < nt; t += 2) {
;             const bool last = (t == nt - 2);
;             const char* a1 = cA + (size_t)(t + 1) * kstep;
;             const char* a2 = last ? nA : cA + (size_t)(t + 2) * kstep; const char* b2 = last ? nB : cB + (size_t)(t + 2) * kstep;
;     ...
;             PG8_LDA(At, 1, 1); PG8_STAGE(PG8_SB(1, 0), b3, voffB); PG8_STAGE(PG8_SB(1, 1), b3 + hstep, voffB); PG8_STAGE(PG8_SA(1, 0), a3, voffA);
;             PG8_WAIT_V(8); PG8_WAIT_L(0); PG8_BAR; PG8_MMA(1, 0, At, B0); PG8_MMA(1, 1, At, B1); PG8_BAR; PG8_SCHED;
	s_add_i32 s4, s41, s24
	v_lshl_add_u64 v[156:157], v[156:157], 0, s[84:85]
	s_mov_b32 m0, s4
	ds_read_b128 v[188:191], v183 offset:49152
	ds_read_b128 v[212:215], v183 offset:50176
	ds_read_b128 v[216:219], v183 offset:51200
	ds_read_b128 v[220:223], v183 offset:52224
	ds_read_b128 v[224:227], v183 offset:53248
	ds_read_b128 v[228:231], v183 offset:54272
	ds_read_b128 v[232:235], v183 offset:55296
	ds_read_b128 v[236:239], v183 offset:56320
	global_load_lds_dwordx4 v[156:157], off
	s_add_i32 m0, s4, 0x2000
	s_add_u32 s2, s2, 0x80080
	v_lshl_add_u64 v[156:157], v[192:193], 0, s[84:85]
	s_addc_u32 s3, s3, 0
	s_add_i32 s4, s42, s24
	global_load_lds_dwordx4 v[156:157], off
	v_lshl_add_u64 v[156:157], s[2:3], 0, v[0:1]
	s_mov_b32 m0, s4
	s_nop 0
	global_load_lds_dwordx4 v[156:157], off
	v_lshl_add_u64 v[156:157], s[2:3], 0, v[146:147]
	s_add_i32 m0, s4, 0x2000
	s_nop 0
	global_load_lds_dwordx4 v[156:157], off
	v_lshl_add_u64 v[156:157], v[240:241], 0, s[84:85]
	s_mov_b32 m0, s29
	s_nop 0
	global_load_lds_dwordx4 v[156:157], off
	v_lshl_add_u64 v[156:157], v[242:243], 0, s[84:85]
	s_mov_b32 m0, s30
	s_nop 0
	global_load_lds_dwordx4 v[156:157], off
	s_waitcnt vmcnt(8)
	s_waitcnt lgkmcnt(0)
	s_barrier
	s_waitcnt lgkmcnt(0)
	v_mfma_f32_16x16x32_bf16 v[78:81], v[50:53], v[188:191], v[78:81]
	v_mfma_f32_16x16x32_bf16 v[74:77], v[66:69], v[188:191], v[74:77]
	v_mfma_f32_16x16x32_bf16 v[62:65], v[50:53], v[216:219], v[62:65]
	v_mfma_f32_16x16x32_bf16 v[58:61], v[66:69], v[216:219], v[58:61]
	v_mfma_f32_16x16x32_bf16 v[38:41], v[50:53], v[224:227], v[38:41]
	v_mfma_f32_16x16x32_bf16 v[34:37], v[66:69], v[224:227], v[34:37]
	v_mfma_f32_16x16x32_bf16 v[14:17], v[50:53], v[232:235], v[14:17]
	v_mfma_f32_16x16x32_bf16 v[10:13], v[66:69], v[232:235], v[10:13]
	v_mfma_f32_16x16x32_bf16 v[78:81], v[54:57], v[212:215], v[78:81]
	v_mfma_f32_16x16x32_bf16 v[74:77], v[70:73], v[212:215], v[74:77]
	v_mfma_f32_16x16x32_bf16 v[62:65], v[54:57], v[220:223], v[62:65]
	v_mfma_f32_16x16x32_bf16 v[58:61], v[70:73], v[220:223], v[58:61]
	v_mfma_f32_16x16x32_bf16 v[38:41], v[54:57], v[228:231], v[38:41]
	v_mfma_f32_16x16x32_bf16 v[34:37], v[70:73], v[228:231], v[34:37]
	v_mfma_f32_16x16x32_bf16 v[14:17], v[54:57], v[236:239], v[14:17]
	v_mfma_f32_16x16x32_bf16 v[10:13], v[70:73], v[236:239], v[10:13]
	v_mfma_f32_16x16x32_bf16 v[26:29], v[168:171], v[188:191], v[26:29]
	v_mfma_f32_16x16x32_bf16 v[70:73], v[172:175], v[212:215], v[26:29]
	v_mfma_f32_16x16x32_bf16 v[26:29], v[176:179], v[188:191], v[30:33]
	v_mfma_f32_16x16x32_bf16 v[66:69], v[184:187], v[212:215], v[26:29]
	v_mfma_f32_16x16x32_bf16 v[26:29], v[168:171], v[216:219], v[42:45]
	v_mfma_f32_16x16x32_bf16 v[54:57], v[172:175], v[220:223], v[26:29]
	v_mfma_f32_16x16x32_bf16 v[26:29], v[176:179], v[216:219], v[46:49]
	v_mfma_f32_16x16x32_bf16 v[22:25], v[168:171], v[224:227], v[22:25]
	v_mfma_f32_16x16x32_bf16 v[18:21], v[176:179], v[224:227], v[18:21]
	v_mfma_f32_16x16x32_bf16 v[6:9], v[168:171], v[232:235], v[6:9]
	v_mfma_f32_16x16x32_bf16 v[2:5], v[176:179], v[232:235], v[2:5]
	v_mfma_f32_16x16x32_bf16 v[50:53], v[184:187], v[220:223], v[26:29]
	v_mfma_f32_16x16x32_bf16 v[22:25], v[172:175], v[228:231], v[22:25]
	v_mfma_f32_16x16x32_bf16 v[18:21], v[184:187], v[228:231], v[18:21]
	v_mfma_f32_16x16x32_bf16 v[6:9], v[172:175], v[236:239], v[6:9]
	v_mfma_f32_16x16x32_bf16 v[2:5], v[184:187], v[236:239], v[2:5]
	s_barrier
	s_add_i32 s40, s40, 2
	s_add_u32 s0, s0, 0x100
	s_addc_u32 s1, s1, 0
	s_add_u32 s38, s38, 0x100
	s_addc_u32 s39, s39, 0
	s_cmp_gt_u32 s40, 29
	s_cbranch_scc0 .LBB0_277
	s_and_b64 vcc, exec, s[14:15]
	s_cbranch_vccz .LBB0_280
	s_barrier

; #define PG8_STAGE(bufoff, gbase, voff) do { _Pragma("unroll") for (int _i = 0; _i < 2; ++_i) \
;         __builtin_amdgcn_global_load_lds((const unsigned*)((const char*)(gbase) + (voff)[_i]), (PG8_LAS unsigned*)(lds + (bufoff) + ldsw + _i * 8192), 16, 0, 0); } while (0)
; #define PG8_LDA(dst, b, h) do { _Pragma("unroll") for (int m = 0; m < 4; ++m) _Pragma("unroll") for (int k = 0; k < 2; ++k) dst[m][k] = *(const PG8_LAS bf16x8*)(lds + PG8_SA(b, h) + aoff + m * 2048 + k * 1024); } while (0)
; #define PG8_LDB(dst, b, h) do { _Pragma("unroll") for (int n = 0; n < 2; ++n) _Pragma("unroll") for (int k = 0; k < 2; ++k) dst[n][k] = *(const PG8_LAS bf16x8*)(lds + PG8_SB(b, h) + boff + n * 2048 + k * 1024); } while (0)
; #define PG8_WAIT_V(n) asm volatile("s_waitcnt vmcnt(" #n ")" ::: "memory")
; #define PG8_WAIT_L(n) asm volatile("s_waitcnt lgkmcnt(" #n ")" ::: "memory")
; #define PG8_BAR __builtin_amdgcn_s_barrier()
; #define PG8_SCHED __builtin_amdgcn_sched_barrier(0)
; template <class Epi, class Sched, bool ALIGN_EPI = false, bool SP2 = false>
; __device__ __forceinline__ void gemm_phase(PG8_LAS unsigned char* lds, const Gemm g, const Sched& S, const Epi& E, int wave_in) {
;     ...
;         const char* nA = has_next ? (const char*)g.A + (size_t)nxt.pm * tstepA : cA; const char* nB = has_next ? (const char*)g.Bt + (size_t)nxt.pn * tstep : cB;
;         for (int t = 0; t < nt; t += 2) {
;             const bool last = (t == nt - 2);
;             const char* a1 = cA + (size_t)(t + 1) * kstep;
;             const char* a2 = last ? nA : cA + (size_t)(t + 2) * kstep; const char* b2 = last ? nB : cB + (size_t)(t + 2) * kstep;
;             const char* a3 = a2 + kstep; const char* b3 = b2 + kstep;
;             if (last && has_next) S.a_ready(nxt);
;             if constexpr (SP2) {
;             PG8_LDB(B0, 0, 0); PG8_LDB(B1, 0, 1); PG8_SCHED; PG8_LDA(At, 0, 0); PG8_STAGE(PG8_SA(1, 1), a1 + hstepA, voffA);
;             PG8_WAIT_V(8); PG8_WAIT_L(0); PG8_BAR; PG8_MMA(0, 0, At, B0); PG8_MMA(0, 1, At, B1); PG8_BAR; PG8_SCHED;
;             PG8_LDA(At, 0, 1); PG8_STAGE(PG8_SB(0, 0), b2, voffB); PG8_STAGE(PG8_SB(0, 1), b2 + hstep, voffB); PG8_STAGE(PG8_SA(0, 0), a2, voffA);
;             PG8_WAIT_V(8); PG8_WAIT_L(0); PG8_BAR; PG8_MMA(1, 0, At, B0); PG8_MMA(1, 1, At, B1); PG8_BAR; PG8_SCHED;
.Lmg_nohook:
	s_add_i32 s43, s6, 2
	s_add_u32 s44, s4, 0x80
	s_addc_u32 s7, s5, 0
	s_add_i32 s46, 0, 0x10000
	s_cmp_eq_u32 s37, s6
	s_cselect_b32 s7, s21, s7
	s_cselect_b32 s6, s20, s44
	s_cselect_b32 s45, s23, s25
	s_cselect_b32 s44, s22, s24
	s_add_i32 s47, 0, 0x14000
	v_add_u32_e32 v168, s46, v149
	v_add_u32_e32 v184, s47, v149
	ds_read_b128 v[140:143], v168
	ds_read_b128 v[144:147], v168 offset:1024
	ds_read_b128 v[154:157], v168 offset:2048
	ds_read_b128 v[168:171], v168 offset:3072
	ds_read_b128 v[172:175], v184
	ds_read_b128 v[176:179], v184 offset:1024
	ds_read_b128 v[180:183], v184 offset:2048
	ds_read_b128 v[184:187], v184 offset:3072
	v_lshl_add_u64 v[192:193], s[4:5], 0, v[136:137]
	s_add_i32 m0, s28, 0xc000
	ds_read_b128 v[188:191], v153
	ds_read_b128 v[212:215], v153 offset:1024
	ds_read_b128 v[216:219], v153 offset:2048
	ds_read_b128 v[220:223], v153 offset:3072
	ds_read_b128 v[224:227], v153 offset:4096
	ds_read_b128 v[228:231], v153 offset:5120
	ds_read_b128 v[232:235], v153 offset:6144
	ds_read_b128 v[236:239], v153 offset:7168
	global_load_lds_dwordx4 v[192:193], off
	v_lshl_add_u64 v[192:193], s[4:5], 0, v[138:139]
	s_add_i32 m0, s28, 0xe000
	s_nop 0
	global_load_lds_dwordx4 v[192:193], off
	s_waitcnt vmcnt(8)
	s_waitcnt lgkmcnt(0)
	s_barrier
	s_waitcnt lgkmcnt(0)
	v_mfma_f32_16x16x32_bf16 v[126:129], v[140:143], v[188:191], v[126:129]
	v_mfma_f32_16x16x32_bf16 v[122:125], v[154:157], v[188:191], v[122:125]
	v_mfma_f32_16x16x32_bf16 v[110:113], v[140:143], v[216:219], v[110:113]
	v_mfma_f32_16x16x32_bf16 v[106:109], v[154:157], v[216:219], v[106:109]
	v_mfma_f32_16x16x32_bf16 v[94:97], v[140:143], v[224:227], v[94:97]
	v_mfma_f32_16x16x32_bf16 v[90:93], v[154:157], v[224:227], v[90:93]
	v_mfma_f32_16x16x32_bf16 v[78:81], v[140:143], v[232:235], v[78:81]
	v_mfma_f32_16x16x32_bf16 v[74:77], v[154:157], v[232:235], v[74:77]
	v_mfma_f32_16x16x32_bf16 v[126:129], v[144:147], v[212:215], v[126:129]
	v_mfma_f32_16x16x32_bf16 v[122:125], v[168:171], v[212:215], v[122:125]
	v_mfma_f32_16x16x32_bf16 v[110:113], v[144:147], v[220:223], v[110:113]
	v_mfma_f32_16x16x32_bf16 v[106:109], v[168:171], v[220:223], v[106:109]
	v_mfma_f32_16x16x32_bf16 v[94:97], v[144:147], v[228:231], v[94:97]
	v_mfma_f32_16x16x32_bf16 v[90:93], v[168:171], v[228:231], v[90:93]
	v_mfma_f32_16x16x32_bf16 v[78:81], v[144:147], v[236:239], v[78:81]
	v_mfma_f32_16x16x32_bf16 v[74:77], v[168:171], v[236:239], v[74:77]
	v_mfma_f32_16x16x32_bf16 v[118:121], v[172:175], v[188:191], v[118:121]
	v_mfma_f32_16x16x32_bf16 v[114:117], v[180:183], v[188:191], v[114:117]
	v_mfma_f32_16x16x32_bf16 v[102:105], v[172:175], v[216:219], v[102:105]
	v_mfma_f32_16x16x32_bf16 v[98:101], v[180:183], v[216:219], v[98:101]
	v_mfma_f32_16x16x32_bf16 v[86:89], v[172:175], v[224:227], v[86:89]
	v_mfma_f32_16x16x32_bf16 v[82:85], v[180:183], v[224:227], v[82:85]
	v_mfma_f32_16x16x32_bf16 v[70:73], v[172:175], v[232:235], v[70:73]
	v_mfma_f32_16x16x32_bf16 v[66:69], v[180:183], v[232:235], v[66:69]
	v_mfma_f32_16x16x32_bf16 v[118:121], v[176:179], v[212:215], v[118:121]
	v_mfma_f32_16x16x32_bf16 v[114:117], v[184:187], v[212:215], v[114:117]
	v_mfma_f32_16x16x32_bf16 v[102:105], v[176:179], v[220:223], v[102:105]
	v_mfma_f32_16x16x32_bf16 v[98:101], v[184:187], v[220:223], v[98:101]
	v_mfma_f32_16x16x32_bf16 v[86:89], v[176:179], v[228:231], v[86:89]
	v_mfma_f32_16x16x32_bf16 v[82:85], v[184:187], v[228:231], v[82:85]
	v_mfma_f32_16x16x32_bf16 v[70:73], v[176:179], v[236:239], v[70:73]
	v_mfma_f32_16x16x32_bf16 v[66:69], v[184:187], v[236:239], v[66:69]
	s_barrier
	s_add_i32 s46, s46, s27
	v_lshl_add_u64 v[192:193], s[44:45], 0, v[0:1]
	s_mov_b32 m0, s46
	ds_read_b128 v[188:191], v153 offset:16384
	ds_read_b128 v[212:215], v153 offset:17408
	ds_read_b128 v[216:219], v153 offset:18432
	ds_read_b128 v[220:223], v153 offset:19456
	ds_read_b128 v[224:227], v153 offset:20480
	ds_read_b128 v[228:231], v153 offset:21504
	ds_read_b128 v[232:235], v153 offset:22528
	ds_read_b128 v[236:239], v153 offset:23552
	global_load_lds_dwordx4 v[192:193], off
	s_add_i32 m0, s46, 0x2000
	v_lshl_add_u64 v[200:201], s[44:45], 0, v[130:131]
	s_add_u32 s44, s44, s78
	s_addc_u32 s45, s45, 0
	s_add_i32 s46, s47, s27
	global_load_lds_dwordx4 v[200:201], off
	v_lshl_add_u64 v[240:241], s[44:45], 0, v[0:1]
	s_mov_b32 m0, s46
	v_lshl_add_u64 v[242:243], s[44:45], 0, v[130:131]
	global_load_lds_dwordx4 v[240:241], off
	s_add_i32 m0, s46, 0x2000
	v_lshl_add_u64 v[244:245], s[6:7], 0, v[134:135]
	global_load_lds_dwordx4 v[242:243], off
	s_mov_b32 m0, s28
	v_lshl_add_u64 v[246:247], s[6:7], 0, v[132:133]
	global_load_lds_dwordx4 v[244:245], off
	s_mov_b32 m0, s29
	s_nop 0
	global_load_lds_dwordx4 v[246:247], off
	s_waitcnt vmcnt(8)
	s_waitcnt lgkmcnt(0)
	s_barrier
; #define PG8_STAGE(bufoff, gbase, voff) do { _Pragma("unroll") for (int _i = 0; _i < 2; ++_i) \
;         __builtin_amdgcn_global_load_lds((const unsigned*)((const char*)(gbase) + (voff)[_i]), (PG8_LAS unsigned*)(lds + (bufoff) + ldsw + _i * 8192), 16, 0, 0); } while (0)
; #define PG8_LDA(dst, b, h) do { _Pragma("unroll") for (int m = 0; m < 4; ++m) _Pragma("unroll") for (int k = 0; k < 2; ++k) dst[m][k] = *(const PG8_LAS bf16x8*)(lds + PG8_SA(b, h) + aoff + m * 2048 + k * 1024); } while (0)
; #define PG8_LDB(dst, b, h) do { _Pragma("unroll") for (int n = 0; n < 2; ++n) _Pragma("unroll") for (int k = 0; k < 2; ++k) dst[n][k] = *(const PG8_LAS bf16x8*)(lds + PG8_SB(b, h) + boff + n * 2048 + k * 1024); } while (0)
; #define PG8_MMA(ai, bj, At, Bt) do { __builtin_amdgcn_s_setprio(1); _Pragma("unroll") for (int m = 0; m < 4; ++m) _Pragma("unroll") for (int n = 0; n < 2; ++n) _Pragma("unroll") for (int k = 0; k < 2; ++k) \
;         acc[ai][bj][m][n] = __builtin_amdgcn_mfma_f32_16x16x32_bf16(Bt[n][k], At[m][k], acc[ai][bj][m][n], 0, 0, 0); __builtin_amdgcn_s_setprio(0); } while (0)
; #define PG8_WAIT_V(n) asm volatile("s_waitcnt vmcnt(" #n ")" ::: "memory")
; #define PG8_WAIT_L(n) asm volatile("s_waitcnt lgkmcnt(" #n ")" ::: "memory")
; #define PG8_BAR __builtin_amdgcn_s_barrier()
; #define PG8_SCHED __builtin_amdgcn_sched_barrier(0)
; template <class Epi, class Sched, bool ALIGN_EPI = false, bool SP2 = false>
; __device__ __forceinline__ void gemm_phase(PG8_LAS unsigned char* lds, const Gemm g, const Sched& S, const Epi& E, int wave_in) {
;     ...
;             PG8_WAIT_V(8); PG8_WAIT_L(0); PG8_BAR; PG8_MMA(1, 0, At, B0); PG8_MMA(1, 1, At, B1); PG8_BAR; PG8_SCHED;
;             PG8_LDB(B0, 1, 0); PG8_LDB(B1, 1, 1); PG8_SCHED; PG8_LDA(At, 1, 0); PG8_STAGE(PG8_SA(0, 1), a2 + hstepA, voffA);
;             PG8_WAIT_V(8); PG8_WAIT_L(0); PG8_BAR; PG8_MMA(0, 0, At, B0); PG8_MMA(0, 1, At, B1); PG8_BAR; PG8_SCHED;
	s_waitcnt lgkmcnt(0)
	v_mfma_f32_16x16x32_bf16 v[62:65], v[140:143], v[188:191], v[62:65]
	v_mfma_f32_16x16x32_bf16 v[58:61], v[154:157], v[188:191], v[58:61]
	v_mfma_f32_16x16x32_bf16 v[46:49], v[140:143], v[216:219], v[46:49]
	v_mfma_f32_16x16x32_bf16 v[42:45], v[154:157], v[216:219], v[42:45]
	v_mfma_f32_16x16x32_bf16 v[30:33], v[140:143], v[224:227], v[30:33]
	v_mfma_f32_16x16x32_bf16 v[26:29], v[154:157], v[224:227], v[26:29]
	v_mfma_f32_16x16x32_bf16 v[14:17], v[140:143], v[232:235], v[14:17]
	v_mfma_f32_16x16x32_bf16 v[10:13], v[154:157], v[232:235], v[10:13]
	v_mfma_f32_16x16x32_bf16 v[62:65], v[144:147], v[212:215], v[62:65]
	v_mfma_f32_16x16x32_bf16 v[58:61], v[168:171], v[212:215], v[58:61]
	v_mfma_f32_16x16x32_bf16 v[46:49], v[144:147], v[220:223], v[46:49]
	v_mfma_f32_16x16x32_bf16 v[42:45], v[168:171], v[220:223], v[42:45]
	v_mfma_f32_16x16x32_bf16 v[30:33], v[144:147], v[228:231], v[30:33]
	v_mfma_f32_16x16x32_bf16 v[26:29], v[168:171], v[228:231], v[26:29]
	v_mfma_f32_16x16x32_bf16 v[14:17], v[144:147], v[236:239], v[14:17]
	v_mfma_f32_16x16x32_bf16 v[10:13], v[168:171], v[236:239], v[10:13]
	v_mfma_f32_16x16x32_bf16 v[54:57], v[172:175], v[188:191], v[54:57]
	v_mfma_f32_16x16x32_bf16 v[50:53], v[180:183], v[188:191], v[50:53]
	v_mfma_f32_16x16x32_bf16 v[38:41], v[172:175], v[216:219], v[38:41]
	v_mfma_f32_16x16x32_bf16 v[34:37], v[180:183], v[216:219], v[34:37]
	v_mfma_f32_16x16x32_bf16 v[22:25], v[172:175], v[224:227], v[22:25]
	v_mfma_f32_16x16x32_bf16 v[18:21], v[180:183], v[224:227], v[18:21]
	v_mfma_f32_16x16x32_bf16 v[6:9], v[172:175], v[232:235], v[6:9]
	v_mfma_f32_16x16x32_bf16 v[2:5], v[180:183], v[232:235], v[2:5]
	v_mfma_f32_16x16x32_bf16 v[54:57], v[176:179], v[212:215], v[54:57]
	v_mfma_f32_16x16x32_bf16 v[50:53], v[184:187], v[212:215], v[50:53]
	v_mfma_f32_16x16x32_bf16 v[38:41], v[176:179], v[220:223], v[38:41]
	v_mfma_f32_16x16x32_bf16 v[34:37], v[184:187], v[220:223], v[34:37]
	v_mfma_f32_16x16x32_bf16 v[22:25], v[176:179], v[228:231], v[22:25]
	v_mfma_f32_16x16x32_bf16 v[18:21], v[184:187], v[228:231], v[18:21]
	v_mfma_f32_16x16x32_bf16 v[6:9], v[176:179], v[236:239], v[6:9]
	v_mfma_f32_16x16x32_bf16 v[2:5], v[184:187], v[236:239], v[2:5]
	s_barrier
	s_add_i32 s44, 0, 0x18000
	s_add_i32 s45, 0, 0x1c000
	v_add_u32_e32 v168, s44, v149
	v_add_u32_e32 v184, s45, v149
	ds_read_b128 v[140:143], v168
	ds_read_b128 v[144:147], v168 offset:1024
	ds_read_b128 v[154:157], v168 offset:2048
	ds_read_b128 v[168:171], v168 offset:3072
	ds_read_b128 v[172:175], v184
	ds_read_b128 v[176:179], v184 offset:1024
	ds_read_b128 v[180:183], v184 offset:2048
	ds_read_b128 v[184:187], v184 offset:3072
	s_add_u32 s6, s6, s78
	s_addc_u32 s7, s7, 0
	s_mov_b32 m0, s30
	v_lshl_add_u64 v[248:249], s[6:7], 0, v[134:135]
	ds_read_b128 v[188:191], v153 offset:32768
	ds_read_b128 v[212:215], v153 offset:33792
	ds_read_b128 v[216:219], v153 offset:34816
	ds_read_b128 v[220:223], v153 offset:35840
	ds_read_b128 v[224:227], v153 offset:36864
	ds_read_b128 v[228:231], v153 offset:37888
	ds_read_b128 v[232:235], v153 offset:38912
	ds_read_b128 v[236:239], v153 offset:39936
	global_load_lds_dwordx4 v[248:249], off
	v_lshl_add_u64 v[248:249], s[6:7], 0, v[132:133]
	s_mov_b32 m0, s31
	s_nop 0
	global_load_lds_dwordx4 v[248:249], off
	s_waitcnt vmcnt(8)
	s_waitcnt lgkmcnt(0)
	s_barrier
	s_waitcnt lgkmcnt(0)
	v_mfma_f32_16x16x32_bf16 v[126:129], v[140:143], v[188:191], v[126:129]
	v_mfma_f32_16x16x32_bf16 v[122:125], v[154:157], v[188:191], v[122:125]
	v_mfma_f32_16x16x32_bf16 v[110:113], v[140:143], v[216:219], v[110:113]
	v_mfma_f32_16x16x32_bf16 v[106:109], v[154:157], v[216:219], v[106:109]
	v_mfma_f32_16x16x32_bf16 v[94:97], v[140:143], v[224:227], v[94:97]
	v_mfma_f32_16x16x32_bf16 v[90:93], v[154:157], v[224:227], v[90:93]
	v_mfma_f32_16x16x32_bf16 v[78:81], v[140:143], v[232:235], v[78:81]
	v_mfma_f32_16x16x32_bf16 v[74:77], v[154:157], v[232:235], v[74:77]
	v_mfma_f32_16x16x32_bf16 v[126:129], v[144:147], v[212:215], v[126:129]
	v_mfma_f32_16x16x32_bf16 v[122:125], v[168:171], v[212:215], v[122:125]
	v_mfma_f32_16x16x32_bf16 v[110:113], v[144:147], v[220:223], v[110:113]
	v_mfma_f32_16x16x32_bf16 v[106:109], v[168:171], v[220:223], v[106:109]
	v_mfma_f32_16x16x32_bf16 v[94:97], v[144:147], v[228:231], v[94:97]
	v_mfma_f32_16x16x32_bf16 v[90:93], v[168:171], v[228:231], v[90:93]
	v_mfma_f32_16x16x32_bf16 v[78:81], v[144:147], v[236:239], v[78:81]
	v_mfma_f32_16x16x32_bf16 v[74:77], v[168:171], v[236:239], v[74:77]
	v_mfma_f32_16x16x32_bf16 v[118:121], v[172:175], v[188:191], v[118:121]
	v_mfma_f32_16x16x32_bf16 v[114:117], v[180:183], v[188:191], v[114:117]
	v_mfma_f32_16x16x32_bf16 v[102:105], v[172:175], v[216:219], v[102:105]
	v_mfma_f32_16x16x32_bf16 v[98:101], v[180:183], v[216:219], v[98:101]
	v_mfma_f32_16x16x32_bf16 v[86:89], v[172:175], v[224:227], v[86:89]
	v_mfma_f32_16x16x32_bf16 v[82:85], v[180:183], v[224:227], v[82:85]
	v_mfma_f32_16x16x32_bf16 v[70:73], v[172:175], v[232:235], v[70:73]
	v_mfma_f32_16x16x32_bf16 v[66:69], v[180:183], v[232:235], v[66:69]
	v_mfma_f32_16x16x32_bf16 v[118:121], v[176:179], v[212:215], v[118:121]
	v_mfma_f32_16x16x32_bf16 v[114:117], v[184:187], v[212:215], v[114:117]
	v_mfma_f32_16x16x32_bf16 v[102:105], v[176:179], v[220:223], v[102:105]
	v_mfma_f32_16x16x32_bf16 v[98:101], v[184:187], v[220:223], v[98:101]
	v_mfma_f32_16x16x32_bf16 v[86:89], v[176:179], v[228:231], v[86:89]
	v_mfma_f32_16x16x32_bf16 v[82:85], v[184:187], v[228:231], v[82:85]
	v_mfma_f32_16x16x32_bf16 v[70:73], v[176:179], v[236:239], v[70:73]
	v_mfma_f32_16x16x32_bf16 v[66:69], v[184:187], v[236:239], v[66:69]
	s_barrier
; #define PG8_STAGE(bufoff, gbase, voff) do { _Pragma("unroll") for (int _i = 0; _i < 2; ++_i) \
;         __builtin_amdgcn_global_load_lds((const unsigned*)((const char*)(gbase) + (voff)[_i]), (PG8_LAS unsigned*)(lds + (bufoff) + ldsw + _i * 8192), 16, 0, 0); } while (0)
; #define PG8_LDA(dst, b, h) do { _Pragma("unroll") for (int m = 0; m < 4; ++m) _Pragma("unroll") for (int k = 0; k < 2; ++k) dst[m][k] = *(const PG8_LAS bf16x8*)(lds + PG8_SA(b, h) + aoff + m * 2048 + k * 1024); } while (0)
; #define PG8_MMA(ai, bj, At, Bt) do { __builtin_amdgcn_s_setprio(1); _Pragma("unroll") for (int m = 0; m < 4; ++m) _Pragma("unroll") for (int n = 0; n < 2; ++n) _Pragma("unroll") for (int k = 0; k < 2; ++k) \
;         acc[ai][bj][m][n] = __builtin_amdgcn_mfma_f32_16x16x32_bf16(Bt[n][k], At[m][k], acc[ai][bj][m][n], 0, 0, 0); __builtin_amdgcn_s_setprio(0); } while (0)
; #define PG8_WAIT_V(n) asm volatile("s_waitcnt vmcnt(" #n ")" ::: "memory")
; #define PG8_WAIT_L(n) asm volatile("s_waitcnt lgkmcnt(" #n ")" ::: "memory")
; #define PG8_BAR __builtin_amdgcn_s_barrier()
; #define PG8_SCHED __builtin_amdgcn_sched_barrier(0)
; template <class Epi, class Sched, bool ALIGN_EPI = false, bool SP2 = false>
; __device__ __forceinline__ void gemm_phase(PG8_LAS unsigned char* lds, const Gemm g, const Sched& S, const Epi& E, int wave_in) {
;     ...
;         for (int t = 0; t < nt; t += 2) {
;     ...
;             PG8_LDA(At, 1, 1); PG8_STAGE(PG8_SB(1, 0), b3, voffB); PG8_STAGE(PG8_SB(1, 1), b3 + hstep, voffB); PG8_STAGE(PG8_SA(1, 0), a3, voffA);
;             PG8_WAIT_V(8); PG8_WAIT_L(0); PG8_BAR; PG8_MMA(1, 0, At, B0); PG8_MMA(1, 1, At, B1); PG8_BAR; PG8_SCHED;
	s_add_i32 s6, s44, s27
	v_lshl_add_u64 v[192:193], v[192:193], 0, s[84:85]
	s_mov_b32 m0, s6
	ds_read_b128 v[188:191], v153 offset:49152
	ds_read_b128 v[212:215], v153 offset:50176
	ds_read_b128 v[216:219], v153 offset:51200
	ds_read_b128 v[220:223], v153 offset:52224
	ds_read_b128 v[224:227], v153 offset:53248
	ds_read_b128 v[228:231], v153 offset:54272
	ds_read_b128 v[232:235], v153 offset:55296
	ds_read_b128 v[236:239], v153 offset:56320
	global_load_lds_dwordx4 v[192:193], off
	v_lshl_add_u64 v[192:193], v[200:201], 0, s[84:85]
	s_add_i32 m0, s6, 0x2000
	s_add_i32 s6, s45, s27
	global_load_lds_dwordx4 v[192:193], off
	v_lshl_add_u64 v[192:193], v[240:241], 0, s[84:85]
	s_mov_b32 m0, s6
	s_nop 0
	global_load_lds_dwordx4 v[192:193], off
	v_lshl_add_u64 v[192:193], v[242:243], 0, s[84:85]
	s_add_i32 m0, s6, 0x2000
	s_nop 0
	global_load_lds_dwordx4 v[192:193], off
	v_lshl_add_u64 v[192:193], v[244:245], 0, s[84:85]
	s_mov_b32 m0, s34
	s_nop 0
	global_load_lds_dwordx4 v[192:193], off
	v_lshl_add_u64 v[192:193], v[246:247], 0, s[84:85]
	s_mov_b32 m0, s35
	s_nop 0
	global_load_lds_dwordx4 v[192:193], off
	s_waitcnt vmcnt(8)
	s_waitcnt lgkmcnt(0)
	s_barrier
	s_waitcnt lgkmcnt(0)
	v_mfma_f32_16x16x32_bf16 v[62:65], v[140:143], v[188:191], v[62:65]
	v_mfma_f32_16x16x32_bf16 v[58:61], v[154:157], v[188:191], v[58:61]
	v_mfma_f32_16x16x32_bf16 v[46:49], v[140:143], v[216:219], v[46:49]
	v_mfma_f32_16x16x32_bf16 v[42:45], v[154:157], v[216:219], v[42:45]
	v_mfma_f32_16x16x32_bf16 v[30:33], v[140:143], v[224:227], v[30:33]
	v_mfma_f32_16x16x32_bf16 v[26:29], v[154:157], v[224:227], v[26:29]
	v_mfma_f32_16x16x32_bf16 v[14:17], v[140:143], v[232:235], v[14:17]
	v_mfma_f32_16x16x32_bf16 v[10:13], v[154:157], v[232:235], v[10:13]
	v_mfma_f32_16x16x32_bf16 v[62:65], v[144:147], v[212:215], v[62:65]
	v_mfma_f32_16x16x32_bf16 v[58:61], v[168:171], v[212:215], v[58:61]
	v_mfma_f32_16x16x32_bf16 v[46:49], v[144:147], v[220:223], v[46:49]
	v_mfma_f32_16x16x32_bf16 v[42:45], v[168:171], v[220:223], v[42:45]
	v_mfma_f32_16x16x32_bf16 v[30:33], v[144:147], v[228:231], v[30:33]
	v_mfma_f32_16x16x32_bf16 v[26:29], v[168:171], v[228:231], v[26:29]
	v_mfma_f32_16x16x32_bf16 v[14:17], v[144:147], v[236:239], v[14:17]
	v_mfma_f32_16x16x32_bf16 v[10:13], v[168:171], v[236:239], v[10:13]
	v_mfma_f32_16x16x32_bf16 v[54:57], v[172:175], v[188:191], v[54:57]
	v_mfma_f32_16x16x32_bf16 v[50:53], v[180:183], v[188:191], v[50:53]
	v_mfma_f32_16x16x32_bf16 v[38:41], v[172:175], v[216:219], v[38:41]
	v_mfma_f32_16x16x32_bf16 v[34:37], v[180:183], v[216:219], v[34:37]
	v_mfma_f32_16x16x32_bf16 v[22:25], v[172:175], v[224:227], v[22:25]
	v_mfma_f32_16x16x32_bf16 v[18:21], v[180:183], v[224:227], v[18:21]
	v_mfma_f32_16x16x32_bf16 v[6:9], v[172:175], v[232:235], v[6:9]
	v_mfma_f32_16x16x32_bf16 v[2:5], v[180:183], v[232:235], v[2:5]
	v_mfma_f32_16x16x32_bf16 v[54:57], v[176:179], v[212:215], v[54:57]
	v_mfma_f32_16x16x32_bf16 v[50:53], v[184:187], v[212:215], v[50:53]
	v_mfma_f32_16x16x32_bf16 v[38:41], v[176:179], v[220:223], v[38:41]
	v_mfma_f32_16x16x32_bf16 v[34:37], v[184:187], v[220:223], v[34:37]
	v_mfma_f32_16x16x32_bf16 v[22:25], v[176:179], v[228:231], v[22:25]
	v_mfma_f32_16x16x32_bf16 v[18:21], v[184:187], v[228:231], v[18:21]
	v_mfma_f32_16x16x32_bf16 v[6:9], v[176:179], v[236:239], v[6:9]
	v_mfma_f32_16x16x32_bf16 v[2:5], v[184:187], v[236:239], v[2:5]
	s_barrier
	s_add_u32 s4, s4, 0x100
	s_addc_u32 s5, s5, 0
	s_add_u32 s24, s24, 0x100
	s_addc_u32 s25, s25, 0
	s_cmp_ge_u32 s43, s36
	s_mov_b32 s6, s43
	s_cbranch_scc0 .LBB0_404
	s_and_b64 vcc, exec, s[16:17]
	s_cbranch_vccz .LBB0_407
	s_barrier
